# as best, but the MFMA wave drops to prio 0 in the shadow of its second-to-last MFMA (no prio instruction after the trailing barrier)
# baseline (speedup 1.0000x reference)
.LBB0_306:
	ds_read_b128 v[166:169], v162
	ds_read_b128 v[170:173], v162 offset:1024
	ds_read_b128 v[174:177], v162 offset:2048
	ds_read_b128 v[180:183], v162 offset:3072
	ds_read_b128 v[184:187], v163
	ds_read_b128 v[188:191], v163 offset:1024
	ds_read_b128 v[192:195], v163 offset:2048
	ds_read_b128 v[196:199], v163 offset:3072
	s_add_u32 s30, s28, 0xfff80080
	s_addc_u32 s31, s29, -1
	s_cmp_eq_u32 s50, 28
	s_cselect_b32 s35, s3, s31
	s_cselect_b32 s34, s21, s30
	s_cselect_b32 s31, s19, s49
	s_cselect_b32 s30, s27, s48
	v_lshl_add_u64 v[160:161], s[28:29], 0, v[152:153]
	s_add_i32 m0, s33, 0xc000
	ds_read_b128 v[200:203], v164
	ds_read_b128 v[204:207], v164 offset:1024
	ds_read_b128 v[208:211], v164 offset:2048
	ds_read_b128 v[212:215], v164 offset:3072
	ds_read_b128 v[216:219], v164 offset:4096
	ds_read_b128 v[220:223], v164 offset:5120
	ds_read_b128 v[224:227], v164 offset:6144
	ds_read_b128 v[228:231], v164 offset:7168
	global_load_lds_dwordx4 v[160:161], off
	v_lshl_add_u64 v[160:161], s[28:29], 0, v[154:155]
	s_add_i32 m0, s33, 0xe000
	s_nop 0
	global_load_lds_dwordx4 v[160:161], off
	s_waitcnt vmcnt(8)
	s_waitcnt lgkmcnt(0)
	s_setprio 1
	s_barrier
	v_mfma_f32_16x16x32_bf16 v[126:129], v[166:169], v[200:203], v[126:129]
	v_mfma_f32_16x16x32_bf16 v[122:125], v[174:177], v[200:203], v[122:125]
	v_mfma_f32_16x16x32_bf16 v[110:113], v[166:169], v[208:211], v[110:113]
	v_mfma_f32_16x16x32_bf16 v[106:109], v[174:177], v[208:211], v[106:109]
	v_mfma_f32_16x16x32_bf16 v[94:97], v[166:169], v[216:219], v[94:97]
	v_mfma_f32_16x16x32_bf16 v[90:93], v[174:177], v[216:219], v[90:93]
	v_mfma_f32_16x16x32_bf16 v[78:81], v[166:169], v[224:227], v[78:81]
	v_mfma_f32_16x16x32_bf16 v[74:77], v[174:177], v[224:227], v[74:77]
	v_mfma_f32_16x16x32_bf16 v[126:129], v[170:173], v[204:207], v[126:129]
	v_mfma_f32_16x16x32_bf16 v[122:125], v[180:183], v[204:207], v[122:125]
	v_mfma_f32_16x16x32_bf16 v[110:113], v[170:173], v[212:215], v[110:113]
	v_mfma_f32_16x16x32_bf16 v[106:109], v[180:183], v[212:215], v[106:109]
	v_mfma_f32_16x16x32_bf16 v[94:97], v[170:173], v[220:223], v[94:97]
	v_mfma_f32_16x16x32_bf16 v[90:93], v[180:183], v[220:223], v[90:93]
	v_mfma_f32_16x16x32_bf16 v[78:81], v[170:173], v[228:231], v[78:81]
	v_mfma_f32_16x16x32_bf16 v[74:77], v[180:183], v[228:231], v[74:77]
	v_mfma_f32_16x16x32_bf16 v[118:121], v[184:187], v[200:203], v[118:121]
	v_mfma_f32_16x16x32_bf16 v[114:117], v[192:195], v[200:203], v[114:117]
	v_mfma_f32_16x16x32_bf16 v[102:105], v[184:187], v[208:211], v[102:105]
	v_mfma_f32_16x16x32_bf16 v[98:101], v[192:195], v[208:211], v[98:101]
	v_mfma_f32_16x16x32_bf16 v[86:89], v[184:187], v[216:219], v[86:89]
	v_mfma_f32_16x16x32_bf16 v[82:85], v[192:195], v[216:219], v[82:85]
	v_mfma_f32_16x16x32_bf16 v[70:73], v[184:187], v[224:227], v[70:73]
	v_mfma_f32_16x16x32_bf16 v[66:69], v[192:195], v[224:227], v[66:69]
	v_mfma_f32_16x16x32_bf16 v[118:121], v[188:191], v[204:207], v[118:121]
	v_mfma_f32_16x16x32_bf16 v[114:117], v[196:199], v[204:207], v[114:117]
	v_mfma_f32_16x16x32_bf16 v[102:105], v[188:191], v[212:215], v[102:105]
	v_mfma_f32_16x16x32_bf16 v[98:101], v[196:199], v[212:215], v[98:101]
	v_mfma_f32_16x16x32_bf16 v[86:89], v[188:191], v[220:223], v[86:89]
	v_mfma_f32_16x16x32_bf16 v[82:85], v[196:199], v[220:223], v[82:85]
	v_mfma_f32_16x16x32_bf16 v[70:73], v[188:191], v[228:231], v[70:73]
	s_setprio 0
	v_mfma_f32_16x16x32_bf16 v[66:69], v[196:199], v[228:231], v[66:69]
	s_barrier
	s_add_i32 s51, s45, s17
	v_lshl_add_u64 v[160:161], s[30:31], 0, v[138:139]
	s_mov_b32 m0, s51
	ds_read_b128 v[200:203], v164 offset:16384
	ds_read_b128 v[204:207], v164 offset:17408
	ds_read_b128 v[208:211], v164 offset:18432
	ds_read_b128 v[212:215], v164 offset:19456
	ds_read_b128 v[216:219], v164 offset:20480
	ds_read_b128 v[220:223], v164 offset:21504
	ds_read_b128 v[224:227], v164 offset:22528
	ds_read_b128 v[228:231], v164 offset:23552
	global_load_lds_dwordx4 v[160:161], off
	s_add_i32 m0, s51, 0x2000
	s_add_u32 s56, s30, 0x80000
	v_lshl_add_u64 v[232:233], s[30:31], 0, v[142:143]
	s_addc_u32 s57, s31, 0
	s_add_i32 s51, s47, s17
	global_load_lds_dwordx4 v[232:233], off
	v_lshl_add_u64 v[234:235], s[56:57], 0, v[138:139]
	s_mov_b32 m0, s51
	v_lshl_add_u64 v[236:237], s[34:35], 0, v[140:141]
	global_load_lds_dwordx4 v[234:235], off
	v_lshl_add_u64 v[234:235], s[56:57], 0, v[142:143]
	s_add_i32 m0, s51, 0x2000
	s_nop 0
	global_load_lds_dwordx4 v[234:235], off
	v_lshl_add_u64 v[234:235], s[34:35], 0, v[136:137]
	s_mov_b32 m0, s33
	s_nop 0
	global_load_lds_dwordx4 v[234:235], off
	s_mov_b32 m0, s36
	s_nop 0
	global_load_lds_dwordx4 v[236:237], off
	s_waitcnt vmcnt(8)
	s_waitcnt lgkmcnt(0)
	s_setprio 1
	s_barrier
	v_mfma_f32_16x16x32_bf16 v[62:65], v[166:169], v[200:203], v[62:65]
	v_mfma_f32_16x16x32_bf16 v[58:61], v[174:177], v[200:203], v[58:61]
	v_mfma_f32_16x16x32_bf16 v[46:49], v[166:169], v[208:211], v[46:49]
	v_mfma_f32_16x16x32_bf16 v[42:45], v[174:177], v[208:211], v[42:45]
	v_mfma_f32_16x16x32_bf16 v[30:33], v[166:169], v[216:219], v[30:33]
	v_mfma_f32_16x16x32_bf16 v[26:29], v[174:177], v[216:219], v[26:29]
	v_mfma_f32_16x16x32_bf16 v[14:17], v[166:169], v[224:227], v[14:17]
	v_mfma_f32_16x16x32_bf16 v[10:13], v[174:177], v[224:227], v[10:13]
	v_mfma_f32_16x16x32_bf16 v[62:65], v[170:173], v[204:207], v[62:65]
	v_mfma_f32_16x16x32_bf16 v[58:61], v[180:183], v[204:207], v[58:61]
	v_mfma_f32_16x16x32_bf16 v[46:49], v[170:173], v[212:215], v[46:49]
	v_mfma_f32_16x16x32_bf16 v[42:45], v[180:183], v[212:215], v[42:45]
	v_mfma_f32_16x16x32_bf16 v[30:33], v[170:173], v[220:223], v[30:33]
	v_mfma_f32_16x16x32_bf16 v[26:29], v[180:183], v[220:223], v[26:29]
	v_mfma_f32_16x16x32_bf16 v[14:17], v[170:173], v[228:231], v[14:17]
	v_mfma_f32_16x16x32_bf16 v[10:13], v[180:183], v[228:231], v[10:13]
	v_mfma_f32_16x16x32_bf16 v[54:57], v[184:187], v[200:203], v[54:57]
	v_mfma_f32_16x16x32_bf16 v[50:53], v[192:195], v[200:203], v[50:53]
	v_mfma_f32_16x16x32_bf16 v[38:41], v[184:187], v[208:211], v[38:41]
	v_mfma_f32_16x16x32_bf16 v[34:37], v[192:195], v[208:211], v[34:37]
	v_mfma_f32_16x16x32_bf16 v[22:25], v[184:187], v[216:219], v[22:25]
	v_mfma_f32_16x16x32_bf16 v[18:21], v[192:195], v[216:219], v[18:21]
	v_mfma_f32_16x16x32_bf16 v[6:9], v[184:187], v[224:227], v[6:9]
	v_mfma_f32_16x16x32_bf16 v[2:5], v[192:195], v[224:227], v[2:5]
	v_mfma_f32_16x16x32_bf16 v[54:57], v[188:191], v[204:207], v[54:57]
	v_mfma_f32_16x16x32_bf16 v[50:53], v[196:199], v[204:207], v[50:53]
	v_mfma_f32_16x16x32_bf16 v[38:41], v[188:191], v[212:215], v[38:41]
	v_mfma_f32_16x16x32_bf16 v[34:37], v[196:199], v[212:215], v[34:37]
	v_mfma_f32_16x16x32_bf16 v[22:25], v[188:191], v[220:223], v[22:25]
	v_mfma_f32_16x16x32_bf16 v[18:21], v[196:199], v[220:223], v[18:21]
	v_mfma_f32_16x16x32_bf16 v[6:9], v[188:191], v[228:231], v[6:9]
	s_setprio 0
	v_mfma_f32_16x16x32_bf16 v[2:5], v[196:199], v[228:231], v[2:5]
	s_barrier
	s_add_i32 s51, 0, 0x18000
	v_add_u32_e32 v144, s51, v135
	s_add_i32 s56, 0, 0x1c000
	ds_read_b128 v[166:169], v144
	ds_read_b128 v[170:173], v144 offset:1024
	ds_read_b128 v[174:177], v144 offset:2048
	ds_read_b128 v[180:183], v144 offset:3072
	v_add_u32_e32 v144, s56, v135
	ds_read_b128 v[184:187], v144
	ds_read_b128 v[188:191], v144 offset:1024
	ds_read_b128 v[192:195], v144 offset:2048
	ds_read_b128 v[196:199], v144 offset:3072
	s_add_u32 s34, s34, 0x80000
	s_addc_u32 s35, s35, 0
	s_mov_b32 m0, s37
	v_lshl_add_u64 v[238:239], s[34:35], 0, v[136:137]
	ds_read_b128 v[200:203], v164 offset:32768
	ds_read_b128 v[204:207], v164 offset:33792
	ds_read_b128 v[208:211], v164 offset:34816
	ds_read_b128 v[212:215], v164 offset:35840
	ds_read_b128 v[216:219], v164 offset:36864
	ds_read_b128 v[220:223], v164 offset:37888
	ds_read_b128 v[224:227], v164 offset:38912
	ds_read_b128 v[228:231], v164 offset:39936
	global_load_lds_dwordx4 v[238:239], off
	v_lshl_add_u64 v[238:239], s[34:35], 0, v[140:141]
	s_mov_b32 m0, s38
	s_nop 0
	global_load_lds_dwordx4 v[238:239], off
	s_waitcnt vmcnt(8)
	s_waitcnt lgkmcnt(0)
	s_setprio 1
	s_barrier
	v_mfma_f32_16x16x32_bf16 v[126:129], v[166:169], v[200:203], v[126:129]
	v_mfma_f32_16x16x32_bf16 v[122:125], v[174:177], v[200:203], v[122:125]
	v_mfma_f32_16x16x32_bf16 v[110:113], v[166:169], v[208:211], v[110:113]
	v_mfma_f32_16x16x32_bf16 v[106:109], v[174:177], v[208:211], v[106:109]
	v_mfma_f32_16x16x32_bf16 v[94:97], v[166:169], v[216:219], v[94:97]
	v_mfma_f32_16x16x32_bf16 v[90:93], v[174:177], v[216:219], v[90:93]
	v_mfma_f32_16x16x32_bf16 v[78:81], v[166:169], v[224:227], v[78:81]
	v_mfma_f32_16x16x32_bf16 v[74:77], v[174:177], v[224:227], v[74:77]
	v_mfma_f32_16x16x32_bf16 v[126:129], v[170:173], v[204:207], v[126:129]
	v_mfma_f32_16x16x32_bf16 v[122:125], v[180:183], v[204:207], v[122:125]
	v_mfma_f32_16x16x32_bf16 v[110:113], v[170:173], v[212:215], v[110:113]
	v_mfma_f32_16x16x32_bf16 v[106:109], v[180:183], v[212:215], v[106:109]
	v_mfma_f32_16x16x32_bf16 v[94:97], v[170:173], v[220:223], v[94:97]
	v_mfma_f32_16x16x32_bf16 v[90:93], v[180:183], v[220:223], v[90:93]
	v_mfma_f32_16x16x32_bf16 v[78:81], v[170:173], v[228:231], v[78:81]
	v_mfma_f32_16x16x32_bf16 v[74:77], v[180:183], v[228:231], v[74:77]
	v_mfma_f32_16x16x32_bf16 v[118:121], v[184:187], v[200:203], v[118:121]
	v_mfma_f32_16x16x32_bf16 v[114:117], v[192:195], v[200:203], v[114:117]
	v_mfma_f32_16x16x32_bf16 v[102:105], v[184:187], v[208:211], v[102:105]
	v_mfma_f32_16x16x32_bf16 v[98:101], v[192:195], v[208:211], v[98:101]
	v_mfma_f32_16x16x32_bf16 v[86:89], v[184:187], v[216:219], v[86:89]
	v_mfma_f32_16x16x32_bf16 v[82:85], v[192:195], v[216:219], v[82:85]
	v_mfma_f32_16x16x32_bf16 v[70:73], v[184:187], v[224:227], v[70:73]
	v_mfma_f32_16x16x32_bf16 v[66:69], v[192:195], v[224:227], v[66:69]
	v_mfma_f32_16x16x32_bf16 v[118:121], v[188:191], v[204:207], v[118:121]
	v_mfma_f32_16x16x32_bf16 v[114:117], v[196:199], v[204:207], v[114:117]
	v_mfma_f32_16x16x32_bf16 v[102:105], v[188:191], v[212:215], v[102:105]
	v_mfma_f32_16x16x32_bf16 v[98:101], v[196:199], v[212:215], v[98:101]
	v_mfma_f32_16x16x32_bf16 v[86:89], v[188:191], v[220:223], v[86:89]
	v_mfma_f32_16x16x32_bf16 v[82:85], v[196:199], v[220:223], v[82:85]
	v_mfma_f32_16x16x32_bf16 v[70:73], v[188:191], v[228:231], v[70:73]
	s_setprio 0
	v_mfma_f32_16x16x32_bf16 v[66:69], v[196:199], v[228:231], v[66:69]
	s_barrier
	s_add_i32 s34, s51, s17
	v_lshl_add_u64 v[160:161], v[160:161], 0, s[6:7]
	s_mov_b32 m0, s34
	ds_read_b128 v[200:203], v164 offset:49152
	ds_read_b128 v[204:207], v164 offset:50176
	ds_read_b128 v[208:211], v164 offset:51200
	ds_read_b128 v[212:215], v164 offset:52224
	ds_read_b128 v[216:219], v164 offset:53248
	ds_read_b128 v[220:223], v164 offset:54272
	ds_read_b128 v[224:227], v164 offset:55296
	ds_read_b128 v[228:231], v164 offset:56320
	global_load_lds_dwordx4 v[160:161], off
	s_add_i32 m0, s34, 0x2000
	s_add_u32 s30, s30, 0x80080
	v_lshl_add_u64 v[160:161], v[232:233], 0, s[6:7]
	s_addc_u32 s31, s31, 0
	s_add_i32 s34, s56, s17
	global_load_lds_dwordx4 v[160:161], off
	v_lshl_add_u64 v[160:161], s[30:31], 0, v[138:139]
	s_mov_b32 m0, s34
	s_nop 0
	global_load_lds_dwordx4 v[160:161], off
	v_lshl_add_u64 v[160:161], s[30:31], 0, v[142:143]
	s_add_i32 m0, s34, 0x2000
	s_nop 0
	global_load_lds_dwordx4 v[160:161], off
	v_lshl_add_u64 v[160:161], v[234:235], 0, s[6:7]
	s_mov_b32 m0, s40
	s_nop 0
	global_load_lds_dwordx4 v[160:161], off
	v_lshl_add_u64 v[160:161], v[236:237], 0, s[6:7]
	s_mov_b32 m0, s41
	s_nop 0
	global_load_lds_dwordx4 v[160:161], off
	s_waitcnt vmcnt(8)
	s_waitcnt lgkmcnt(0)
	s_setprio 1
	s_barrier
	v_mfma_f32_16x16x32_bf16 v[62:65], v[166:169], v[200:203], v[62:65]
	v_mfma_f32_16x16x32_bf16 v[58:61], v[174:177], v[200:203], v[58:61]
	v_mfma_f32_16x16x32_bf16 v[46:49], v[166:169], v[208:211], v[46:49]
	v_mfma_f32_16x16x32_bf16 v[42:45], v[174:177], v[208:211], v[42:45]
	v_mfma_f32_16x16x32_bf16 v[30:33], v[166:169], v[216:219], v[30:33]
	v_mfma_f32_16x16x32_bf16 v[26:29], v[174:177], v[216:219], v[26:29]
	v_mfma_f32_16x16x32_bf16 v[14:17], v[166:169], v[224:227], v[14:17]
	v_mfma_f32_16x16x32_bf16 v[10:13], v[174:177], v[224:227], v[10:13]
	v_mfma_f32_16x16x32_bf16 v[62:65], v[170:173], v[204:207], v[62:65]
	v_mfma_f32_16x16x32_bf16 v[58:61], v[180:183], v[204:207], v[58:61]
	v_mfma_f32_16x16x32_bf16 v[46:49], v[170:173], v[212:215], v[46:49]
	v_mfma_f32_16x16x32_bf16 v[42:45], v[180:183], v[212:215], v[42:45]
	v_mfma_f32_16x16x32_bf16 v[30:33], v[170:173], v[220:223], v[30:33]
	v_mfma_f32_16x16x32_bf16 v[26:29], v[180:183], v[220:223], v[26:29]
	v_mfma_f32_16x16x32_bf16 v[14:17], v[170:173], v[228:231], v[14:17]
	v_mfma_f32_16x16x32_bf16 v[10:13], v[180:183], v[228:231], v[10:13]
	v_mfma_f32_16x16x32_bf16 v[54:57], v[184:187], v[200:203], v[54:57]
	v_mfma_f32_16x16x32_bf16 v[50:53], v[192:195], v[200:203], v[50:53]
	v_mfma_f32_16x16x32_bf16 v[38:41], v[184:187], v[208:211], v[38:41]
	v_mfma_f32_16x16x32_bf16 v[34:37], v[192:195], v[208:211], v[34:37]
	v_mfma_f32_16x16x32_bf16 v[22:25], v[184:187], v[216:219], v[22:25]
	v_mfma_f32_16x16x32_bf16 v[18:21], v[192:195], v[216:219], v[18:21]
	v_mfma_f32_16x16x32_bf16 v[6:9], v[184:187], v[224:227], v[6:9]
	v_mfma_f32_16x16x32_bf16 v[2:5], v[192:195], v[224:227], v[2:5]
	v_mfma_f32_16x16x32_bf16 v[54:57], v[188:191], v[204:207], v[54:57]
	v_mfma_f32_16x16x32_bf16 v[50:53], v[196:199], v[204:207], v[50:53]
	v_mfma_f32_16x16x32_bf16 v[38:41], v[188:191], v[212:215], v[38:41]
	v_mfma_f32_16x16x32_bf16 v[34:37], v[196:199], v[212:215], v[34:37]
	v_mfma_f32_16x16x32_bf16 v[22:25], v[188:191], v[220:223], v[22:25]
	v_mfma_f32_16x16x32_bf16 v[18:21], v[196:199], v[220:223], v[18:21]
	v_mfma_f32_16x16x32_bf16 v[6:9], v[188:191], v[228:231], v[6:9]
	s_setprio 0
	v_mfma_f32_16x16x32_bf16 v[2:5], v[196:199], v[228:231], v[2:5]
	s_barrier
	s_add_i32 s50, s50, 2
	s_add_u32 s28, s28, 0x100
	s_addc_u32 s29, s29, 0
	s_add_u32 s48, s48, 0x100
	s_addc_u32 s49, s49, 0
	s_cmp_gt_u32 s50, 29
	s_cbranch_scc0 .LBB0_306
	s_and_b64 vcc, exec, s[8:9]
	s_cbranch_vccz .LBB0_314
	s_barrier
	v_lshl_add_u32 v160, s26, 8, v133
	s_cmp_gt_i32 s2, 35
	s_mov_b64 s[26:27], -1
	s_cbranch_scc1 .LBB0_315

.LBB0_986:
	ds_read_b128 v[148:151], v155
	ds_read_b128 v[158:161], v155 offset:1024
	ds_read_b128 v[162:165], v155 offset:2048
	ds_read_b128 v[166:169], v155 offset:3072
	ds_read_b128 v[170:173], v156
	ds_read_b128 v[174:177], v156 offset:1024
	ds_read_b128 v[180:183], v156 offset:2048
	ds_read_b128 v[184:187], v156 offset:3072
	s_add_u32 s26, s24, 0xfffc0080
	s_addc_u32 s27, s25, -1
	s_cmp_eq_u32 s49, 12
	s_cselect_b32 s29, s17, s27
	s_cselect_b32 s28, s45, s26
	s_cselect_b32 s27, s15, s48
	s_cselect_b32 s26, s46, s47
	v_lshl_add_u64 v[220:221], s[24:25], 0, v[138:139]
	s_add_i32 m0, s23, 0xc000
	ds_read_b128 v[188:191], v157
	ds_read_b128 v[192:195], v157 offset:1024
	ds_read_b128 v[196:199], v157 offset:2048
	ds_read_b128 v[200:203], v157 offset:3072
	ds_read_b128 v[204:207], v157 offset:4096
	ds_read_b128 v[208:211], v157 offset:5120
	ds_read_b128 v[212:215], v157 offset:6144
	ds_read_b128 v[216:219], v157 offset:7168
	global_load_lds_dwordx4 v[220:221], off
	v_lshl_add_u64 v[220:221], s[24:25], 0, v[140:141]
	s_add_i32 m0, s23, 0xe000
	s_nop 0
	global_load_lds_dwordx4 v[220:221], off
	s_waitcnt vmcnt(8)
	s_waitcnt lgkmcnt(0)
	s_setprio 1
	s_barrier
	v_mfma_f32_16x16x32_bf16 v[126:129], v[148:151], v[188:191], v[126:129]
	v_mfma_f32_16x16x32_bf16 v[122:125], v[162:165], v[188:191], v[122:125]
	v_mfma_f32_16x16x32_bf16 v[110:113], v[148:151], v[196:199], v[110:113]
	v_mfma_f32_16x16x32_bf16 v[106:109], v[162:165], v[196:199], v[106:109]
	v_mfma_f32_16x16x32_bf16 v[94:97], v[148:151], v[204:207], v[94:97]
	v_mfma_f32_16x16x32_bf16 v[90:93], v[162:165], v[204:207], v[90:93]
	v_mfma_f32_16x16x32_bf16 v[78:81], v[148:151], v[212:215], v[78:81]
	v_mfma_f32_16x16x32_bf16 v[74:77], v[162:165], v[212:215], v[74:77]
	v_mfma_f32_16x16x32_bf16 v[126:129], v[158:161], v[192:195], v[126:129]
	v_mfma_f32_16x16x32_bf16 v[122:125], v[166:169], v[192:195], v[122:125]
	v_mfma_f32_16x16x32_bf16 v[110:113], v[158:161], v[200:203], v[110:113]
	v_mfma_f32_16x16x32_bf16 v[106:109], v[166:169], v[200:203], v[106:109]
	v_mfma_f32_16x16x32_bf16 v[94:97], v[158:161], v[208:211], v[94:97]
	v_mfma_f32_16x16x32_bf16 v[90:93], v[166:169], v[208:211], v[90:93]
	v_mfma_f32_16x16x32_bf16 v[78:81], v[158:161], v[216:219], v[78:81]
	v_mfma_f32_16x16x32_bf16 v[74:77], v[166:169], v[216:219], v[74:77]
	v_mfma_f32_16x16x32_bf16 v[118:121], v[170:173], v[188:191], v[118:121]
	v_mfma_f32_16x16x32_bf16 v[114:117], v[180:183], v[188:191], v[114:117]
	v_mfma_f32_16x16x32_bf16 v[102:105], v[170:173], v[196:199], v[102:105]
	v_mfma_f32_16x16x32_bf16 v[98:101], v[180:183], v[196:199], v[98:101]
	v_mfma_f32_16x16x32_bf16 v[86:89], v[170:173], v[204:207], v[86:89]
	v_mfma_f32_16x16x32_bf16 v[82:85], v[180:183], v[204:207], v[82:85]
	v_mfma_f32_16x16x32_bf16 v[70:73], v[170:173], v[212:215], v[70:73]
	v_mfma_f32_16x16x32_bf16 v[66:69], v[180:183], v[212:215], v[66:69]
	v_mfma_f32_16x16x32_bf16 v[118:121], v[174:177], v[192:195], v[118:121]
	v_mfma_f32_16x16x32_bf16 v[114:117], v[184:187], v[192:195], v[114:117]
	v_mfma_f32_16x16x32_bf16 v[102:105], v[174:177], v[200:203], v[102:105]
	v_mfma_f32_16x16x32_bf16 v[98:101], v[184:187], v[200:203], v[98:101]
	v_mfma_f32_16x16x32_bf16 v[86:89], v[174:177], v[208:211], v[86:89]
	v_mfma_f32_16x16x32_bf16 v[82:85], v[184:187], v[208:211], v[82:85]
	v_mfma_f32_16x16x32_bf16 v[70:73], v[174:177], v[216:219], v[70:73]
	s_setprio 0
	v_mfma_f32_16x16x32_bf16 v[66:69], v[184:187], v[216:219], v[66:69]
	s_barrier
	s_add_i32 s50, s42, s30
	v_lshl_add_u64 v[220:221], s[26:27], 0, v[134:135]
	s_mov_b32 m0, s50
	ds_read_b128 v[188:191], v157 offset:16384
	ds_read_b128 v[192:195], v157 offset:17408
	ds_read_b128 v[196:199], v157 offset:18432
	ds_read_b128 v[200:203], v157 offset:19456
	ds_read_b128 v[204:207], v157 offset:20480
	ds_read_b128 v[208:211], v157 offset:21504
	ds_read_b128 v[212:215], v157 offset:22528
	ds_read_b128 v[216:219], v157 offset:23552
	global_load_lds_dwordx4 v[220:221], off
	s_add_i32 m0, s50, 0x2000
	s_add_u32 s50, s26, 0x40000
	v_lshl_add_u64 v[222:223], s[26:27], 0, v[130:131]
	s_addc_u32 s51, s27, 0
	s_add_i32 s56, s43, s30
	global_load_lds_dwordx4 v[222:223], off
	v_lshl_add_u64 v[224:225], s[50:51], 0, v[134:135]
	s_mov_b32 m0, s56
	v_lshl_add_u64 v[226:227], s[28:29], 0, v[132:133]
	global_load_lds_dwordx4 v[224:225], off
	v_lshl_add_u64 v[224:225], s[50:51], 0, v[130:131]
	s_add_i32 m0, s56, 0x2000
	s_nop 0
	global_load_lds_dwordx4 v[224:225], off
	v_lshl_add_u64 v[224:225], s[28:29], 0, v[136:137]
	s_mov_b32 m0, s23
	s_nop 0
	global_load_lds_dwordx4 v[224:225], off
	s_mov_b32 m0, s34
	s_nop 0
	global_load_lds_dwordx4 v[226:227], off
	s_waitcnt vmcnt(8)
	s_waitcnt lgkmcnt(0)
	s_setprio 1
	s_barrier
	v_mfma_f32_16x16x32_bf16 v[62:65], v[148:151], v[188:191], v[62:65]
	v_mfma_f32_16x16x32_bf16 v[58:61], v[162:165], v[188:191], v[58:61]
	v_mfma_f32_16x16x32_bf16 v[46:49], v[148:151], v[196:199], v[46:49]
	v_mfma_f32_16x16x32_bf16 v[42:45], v[162:165], v[196:199], v[42:45]
	v_mfma_f32_16x16x32_bf16 v[30:33], v[148:151], v[204:207], v[30:33]
	v_mfma_f32_16x16x32_bf16 v[26:29], v[162:165], v[204:207], v[26:29]
	v_mfma_f32_16x16x32_bf16 v[14:17], v[148:151], v[212:215], v[14:17]
	v_mfma_f32_16x16x32_bf16 v[10:13], v[162:165], v[212:215], v[10:13]
	v_mfma_f32_16x16x32_bf16 v[62:65], v[158:161], v[192:195], v[62:65]
	v_mfma_f32_16x16x32_bf16 v[58:61], v[166:169], v[192:195], v[58:61]
	v_mfma_f32_16x16x32_bf16 v[46:49], v[158:161], v[200:203], v[46:49]
	v_mfma_f32_16x16x32_bf16 v[42:45], v[166:169], v[200:203], v[42:45]
	v_mfma_f32_16x16x32_bf16 v[30:33], v[158:161], v[208:211], v[30:33]
	v_mfma_f32_16x16x32_bf16 v[26:29], v[166:169], v[208:211], v[26:29]
	v_mfma_f32_16x16x32_bf16 v[14:17], v[158:161], v[216:219], v[14:17]
	v_mfma_f32_16x16x32_bf16 v[10:13], v[166:169], v[216:219], v[10:13]
	v_mfma_f32_16x16x32_bf16 v[54:57], v[170:173], v[188:191], v[54:57]
	v_mfma_f32_16x16x32_bf16 v[50:53], v[180:183], v[188:191], v[50:53]
	v_mfma_f32_16x16x32_bf16 v[38:41], v[170:173], v[196:199], v[38:41]
	v_mfma_f32_16x16x32_bf16 v[34:37], v[180:183], v[196:199], v[34:37]
	v_mfma_f32_16x16x32_bf16 v[22:25], v[170:173], v[204:207], v[22:25]
	v_mfma_f32_16x16x32_bf16 v[18:21], v[180:183], v[204:207], v[18:21]
	v_mfma_f32_16x16x32_bf16 v[6:9], v[170:173], v[212:215], v[6:9]
	v_mfma_f32_16x16x32_bf16 v[2:5], v[180:183], v[212:215], v[2:5]
	v_mfma_f32_16x16x32_bf16 v[54:57], v[174:177], v[192:195], v[54:57]
	v_mfma_f32_16x16x32_bf16 v[50:53], v[184:187], v[192:195], v[50:53]
	v_mfma_f32_16x16x32_bf16 v[38:41], v[174:177], v[200:203], v[38:41]
	v_mfma_f32_16x16x32_bf16 v[34:37], v[184:187], v[200:203], v[34:37]
	v_mfma_f32_16x16x32_bf16 v[22:25], v[174:177], v[208:211], v[22:25]
	v_mfma_f32_16x16x32_bf16 v[18:21], v[184:187], v[208:211], v[18:21]
	v_mfma_f32_16x16x32_bf16 v[6:9], v[174:177], v[216:219], v[6:9]
	s_setprio 0
	v_mfma_f32_16x16x32_bf16 v[2:5], v[184:187], v[216:219], v[2:5]
	s_barrier
	s_add_i32 s50, 0, 0x18000
	s_add_i32 s51, 0, 0x1c000
	v_add_u32_e32 v166, s50, v153
	v_add_u32_e32 v179, s51, v153
	ds_read_b128 v[148:151], v166
	ds_read_b128 v[158:161], v166 offset:1024
	ds_read_b128 v[162:165], v166 offset:2048
	ds_read_b128 v[166:169], v166 offset:3072
	ds_read_b128 v[170:173], v179
	ds_read_b128 v[174:177], v179 offset:1024
	ds_read_b128 v[180:183], v179 offset:2048
	ds_read_b128 v[184:187], v179 offset:3072
	s_add_u32 s28, s28, 0x40000
	s_addc_u32 s29, s29, 0
	s_mov_b32 m0, s35
	v_lshl_add_u64 v[228:229], s[28:29], 0, v[136:137]
	ds_read_b128 v[188:191], v157 offset:32768
	ds_read_b128 v[192:195], v157 offset:33792
	ds_read_b128 v[196:199], v157 offset:34816
	ds_read_b128 v[200:203], v157 offset:35840
	ds_read_b128 v[204:207], v157 offset:36864
	ds_read_b128 v[208:211], v157 offset:37888
	ds_read_b128 v[212:215], v157 offset:38912
	ds_read_b128 v[216:219], v157 offset:39936
	global_load_lds_dwordx4 v[228:229], off
	v_lshl_add_u64 v[228:229], s[28:29], 0, v[132:133]
	s_mov_b32 m0, s36
	s_nop 0
	global_load_lds_dwordx4 v[228:229], off
	s_waitcnt vmcnt(8)
	s_waitcnt lgkmcnt(0)
	s_setprio 1
	s_barrier
	v_mfma_f32_16x16x32_bf16 v[126:129], v[148:151], v[188:191], v[126:129]
	v_mfma_f32_16x16x32_bf16 v[122:125], v[162:165], v[188:191], v[122:125]
	v_mfma_f32_16x16x32_bf16 v[110:113], v[148:151], v[196:199], v[110:113]
	v_mfma_f32_16x16x32_bf16 v[106:109], v[162:165], v[196:199], v[106:109]
	v_mfma_f32_16x16x32_bf16 v[94:97], v[148:151], v[204:207], v[94:97]
	v_mfma_f32_16x16x32_bf16 v[90:93], v[162:165], v[204:207], v[90:93]
	v_mfma_f32_16x16x32_bf16 v[78:81], v[148:151], v[212:215], v[78:81]
	v_mfma_f32_16x16x32_bf16 v[74:77], v[162:165], v[212:215], v[74:77]
	v_mfma_f32_16x16x32_bf16 v[126:129], v[158:161], v[192:195], v[126:129]
	v_mfma_f32_16x16x32_bf16 v[122:125], v[166:169], v[192:195], v[122:125]
	v_mfma_f32_16x16x32_bf16 v[110:113], v[158:161], v[200:203], v[110:113]
	v_mfma_f32_16x16x32_bf16 v[106:109], v[166:169], v[200:203], v[106:109]
	v_mfma_f32_16x16x32_bf16 v[94:97], v[158:161], v[208:211], v[94:97]
	v_mfma_f32_16x16x32_bf16 v[90:93], v[166:169], v[208:211], v[90:93]
	v_mfma_f32_16x16x32_bf16 v[78:81], v[158:161], v[216:219], v[78:81]
	v_mfma_f32_16x16x32_bf16 v[74:77], v[166:169], v[216:219], v[74:77]
	v_mfma_f32_16x16x32_bf16 v[118:121], v[170:173], v[188:191], v[118:121]
	v_mfma_f32_16x16x32_bf16 v[114:117], v[180:183], v[188:191], v[114:117]
	v_mfma_f32_16x16x32_bf16 v[102:105], v[170:173], v[196:199], v[102:105]
	v_mfma_f32_16x16x32_bf16 v[98:101], v[180:183], v[196:199], v[98:101]
	v_mfma_f32_16x16x32_bf16 v[86:89], v[170:173], v[204:207], v[86:89]
	v_mfma_f32_16x16x32_bf16 v[82:85], v[180:183], v[204:207], v[82:85]
	v_mfma_f32_16x16x32_bf16 v[70:73], v[170:173], v[212:215], v[70:73]
	v_mfma_f32_16x16x32_bf16 v[66:69], v[180:183], v[212:215], v[66:69]
	v_mfma_f32_16x16x32_bf16 v[118:121], v[174:177], v[192:195], v[118:121]
	v_mfma_f32_16x16x32_bf16 v[114:117], v[184:187], v[192:195], v[114:117]
	v_mfma_f32_16x16x32_bf16 v[102:105], v[174:177], v[200:203], v[102:105]
	v_mfma_f32_16x16x32_bf16 v[98:101], v[184:187], v[200:203], v[98:101]
	v_mfma_f32_16x16x32_bf16 v[86:89], v[174:177], v[208:211], v[86:89]
	v_mfma_f32_16x16x32_bf16 v[82:85], v[184:187], v[208:211], v[82:85]
	v_mfma_f32_16x16x32_bf16 v[70:73], v[174:177], v[216:219], v[70:73]
	s_setprio 0
	v_mfma_f32_16x16x32_bf16 v[66:69], v[184:187], v[216:219], v[66:69]
	s_barrier
	s_add_i32 s28, s50, s30
	v_lshl_add_u64 v[220:221], v[220:221], 0, s[4:5]
	s_mov_b32 m0, s28
	ds_read_b128 v[188:191], v157 offset:49152
	ds_read_b128 v[192:195], v157 offset:50176
	ds_read_b128 v[196:199], v157 offset:51200
	ds_read_b128 v[200:203], v157 offset:52224
	ds_read_b128 v[204:207], v157 offset:53248
	ds_read_b128 v[208:211], v157 offset:54272
	ds_read_b128 v[212:215], v157 offset:55296
	ds_read_b128 v[216:219], v157 offset:56320
	global_load_lds_dwordx4 v[220:221], off
	s_add_i32 m0, s28, 0x2000
	s_add_u32 s26, s26, 0x40080
	v_lshl_add_u64 v[220:221], v[222:223], 0, s[4:5]
	s_addc_u32 s27, s27, 0
	s_add_i32 s28, s51, s30
	global_load_lds_dwordx4 v[220:221], off
	v_lshl_add_u64 v[220:221], s[26:27], 0, v[134:135]
	s_mov_b32 m0, s28
	s_nop 0
	global_load_lds_dwordx4 v[220:221], off
	v_lshl_add_u64 v[220:221], s[26:27], 0, v[130:131]
	s_add_i32 m0, s28, 0x2000
	s_nop 0
	global_load_lds_dwordx4 v[220:221], off
	v_lshl_add_u64 v[220:221], v[224:225], 0, s[4:5]
	s_mov_b32 m0, s38
	s_nop 0
	global_load_lds_dwordx4 v[220:221], off
	v_lshl_add_u64 v[220:221], v[226:227], 0, s[4:5]
	s_mov_b32 m0, s39
	s_nop 0
	global_load_lds_dwordx4 v[220:221], off
	s_waitcnt vmcnt(8)
	s_waitcnt lgkmcnt(0)
	s_setprio 1
	s_barrier
	v_mfma_f32_16x16x32_bf16 v[62:65], v[148:151], v[188:191], v[62:65]
	v_mfma_f32_16x16x32_bf16 v[58:61], v[162:165], v[188:191], v[58:61]
	v_mfma_f32_16x16x32_bf16 v[46:49], v[148:151], v[196:199], v[46:49]
	v_mfma_f32_16x16x32_bf16 v[42:45], v[162:165], v[196:199], v[42:45]
	v_mfma_f32_16x16x32_bf16 v[30:33], v[148:151], v[204:207], v[30:33]
	v_mfma_f32_16x16x32_bf16 v[26:29], v[162:165], v[204:207], v[26:29]
	v_mfma_f32_16x16x32_bf16 v[14:17], v[148:151], v[212:215], v[14:17]
	v_mfma_f32_16x16x32_bf16 v[10:13], v[162:165], v[212:215], v[10:13]
	v_mfma_f32_16x16x32_bf16 v[62:65], v[158:161], v[192:195], v[62:65]
	v_mfma_f32_16x16x32_bf16 v[58:61], v[166:169], v[192:195], v[58:61]
	v_mfma_f32_16x16x32_bf16 v[46:49], v[158:161], v[200:203], v[46:49]
	v_mfma_f32_16x16x32_bf16 v[42:45], v[166:169], v[200:203], v[42:45]
	v_mfma_f32_16x16x32_bf16 v[30:33], v[158:161], v[208:211], v[30:33]
	v_mfma_f32_16x16x32_bf16 v[26:29], v[166:169], v[208:211], v[26:29]
	v_mfma_f32_16x16x32_bf16 v[14:17], v[158:161], v[216:219], v[14:17]
	v_mfma_f32_16x16x32_bf16 v[10:13], v[166:169], v[216:219], v[10:13]
	v_mfma_f32_16x16x32_bf16 v[54:57], v[170:173], v[188:191], v[54:57]
	v_mfma_f32_16x16x32_bf16 v[50:53], v[180:183], v[188:191], v[50:53]
	v_mfma_f32_16x16x32_bf16 v[38:41], v[170:173], v[196:199], v[38:41]
	v_mfma_f32_16x16x32_bf16 v[34:37], v[180:183], v[196:199], v[34:37]
	v_mfma_f32_16x16x32_bf16 v[22:25], v[170:173], v[204:207], v[22:25]
	v_mfma_f32_16x16x32_bf16 v[18:21], v[180:183], v[204:207], v[18:21]
	v_mfma_f32_16x16x32_bf16 v[6:9], v[170:173], v[212:215], v[6:9]
	v_mfma_f32_16x16x32_bf16 v[2:5], v[180:183], v[212:215], v[2:5]
	v_mfma_f32_16x16x32_bf16 v[54:57], v[174:177], v[192:195], v[54:57]
	v_mfma_f32_16x16x32_bf16 v[50:53], v[184:187], v[192:195], v[50:53]
	v_mfma_f32_16x16x32_bf16 v[38:41], v[174:177], v[200:203], v[38:41]
	v_mfma_f32_16x16x32_bf16 v[34:37], v[184:187], v[200:203], v[34:37]
	v_mfma_f32_16x16x32_bf16 v[22:25], v[174:177], v[208:211], v[22:25]
	v_mfma_f32_16x16x32_bf16 v[18:21], v[184:187], v[208:211], v[18:21]
	v_mfma_f32_16x16x32_bf16 v[6:9], v[174:177], v[216:219], v[6:9]
	s_setprio 0
	v_mfma_f32_16x16x32_bf16 v[2:5], v[184:187], v[216:219], v[2:5]
	s_barrier
	s_add_i32 s49, s49, 2
	s_add_u32 s24, s24, 0x100
	s_addc_u32 s25, s25, 0
	s_add_u32 s47, s47, 0x100
	s_addc_u32 s48, s48, 0
	s_cmp_gt_u32 s49, 13
	s_cbranch_scc0 .LBB0_986
	s_and_b64 vcc, exec, s[8:9]
	s_cbranch_vccz .LBB0_989
	s_barrier

.LBB0_1054:
	ds_read_b128 v[148:151], v155
	ds_read_b128 v[158:161], v155 offset:1024
	ds_read_b128 v[162:165], v155 offset:2048
	ds_read_b128 v[166:169], v155 offset:3072
	ds_read_b128 v[170:173], v156
	ds_read_b128 v[174:177], v156 offset:1024
	ds_read_b128 v[180:183], v156 offset:2048
	ds_read_b128 v[184:187], v156 offset:3072
	s_add_u32 s26, s24, 0xfffc0080
	s_addc_u32 s27, s25, -1
	s_cmp_eq_u32 s50, 12
	s_cselect_b32 s29, s17, s27
	s_cselect_b32 s28, s46, s26
	s_cselect_b32 s27, s15, s49
	s_cselect_b32 s26, s47, s48
	v_lshl_add_u64 v[220:221], s[24:25], 0, v[138:139]
	s_add_i32 m0, s23, 0xc000
	ds_read_b128 v[188:191], v157
	ds_read_b128 v[192:195], v157 offset:1024
	ds_read_b128 v[196:199], v157 offset:2048
	ds_read_b128 v[200:203], v157 offset:3072
	ds_read_b128 v[204:207], v157 offset:4096
	ds_read_b128 v[208:211], v157 offset:5120
	ds_read_b128 v[212:215], v157 offset:6144
	ds_read_b128 v[216:219], v157 offset:7168
	global_load_lds_dwordx4 v[220:221], off
	v_lshl_add_u64 v[220:221], s[24:25], 0, v[140:141]
	s_add_i32 m0, s23, 0xe000
	s_nop 0
	global_load_lds_dwordx4 v[220:221], off
	s_waitcnt vmcnt(8)
	s_waitcnt lgkmcnt(0)
	s_setprio 1
	s_barrier
	v_mfma_f32_16x16x32_bf16 v[118:121], v[148:151], v[188:191], v[118:121]
	v_mfma_f32_16x16x32_bf16 v[114:117], v[162:165], v[188:191], v[114:117]
	v_mfma_f32_16x16x32_bf16 v[102:105], v[148:151], v[196:199], v[102:105]
	v_mfma_f32_16x16x32_bf16 v[98:101], v[162:165], v[196:199], v[98:101]
	v_mfma_f32_16x16x32_bf16 v[86:89], v[148:151], v[204:207], v[86:89]
	v_mfma_f32_16x16x32_bf16 v[82:85], v[162:165], v[204:207], v[82:85]
	v_mfma_f32_16x16x32_bf16 v[70:73], v[148:151], v[212:215], v[70:73]
	v_mfma_f32_16x16x32_bf16 v[66:69], v[162:165], v[212:215], v[66:69]
	v_mfma_f32_16x16x32_bf16 v[118:121], v[158:161], v[192:195], v[118:121]
	v_mfma_f32_16x16x32_bf16 v[114:117], v[166:169], v[192:195], v[114:117]
	v_mfma_f32_16x16x32_bf16 v[102:105], v[158:161], v[200:203], v[102:105]
	v_mfma_f32_16x16x32_bf16 v[98:101], v[166:169], v[200:203], v[98:101]
	v_mfma_f32_16x16x32_bf16 v[86:89], v[158:161], v[208:211], v[86:89]
	v_mfma_f32_16x16x32_bf16 v[82:85], v[166:169], v[208:211], v[82:85]
	v_mfma_f32_16x16x32_bf16 v[70:73], v[158:161], v[216:219], v[70:73]
	v_mfma_f32_16x16x32_bf16 v[66:69], v[166:169], v[216:219], v[66:69]
	v_mfma_f32_16x16x32_bf16 v[126:129], v[170:173], v[188:191], v[126:129]
	v_mfma_f32_16x16x32_bf16 v[122:125], v[180:183], v[188:191], v[122:125]
	v_mfma_f32_16x16x32_bf16 v[110:113], v[170:173], v[196:199], v[110:113]
	v_mfma_f32_16x16x32_bf16 v[106:109], v[180:183], v[196:199], v[106:109]
	v_mfma_f32_16x16x32_bf16 v[94:97], v[170:173], v[204:207], v[94:97]
	v_mfma_f32_16x16x32_bf16 v[90:93], v[180:183], v[204:207], v[90:93]
	v_mfma_f32_16x16x32_bf16 v[78:81], v[170:173], v[212:215], v[78:81]
	v_mfma_f32_16x16x32_bf16 v[74:77], v[180:183], v[212:215], v[74:77]
	v_mfma_f32_16x16x32_bf16 v[126:129], v[174:177], v[192:195], v[126:129]
	v_mfma_f32_16x16x32_bf16 v[122:125], v[184:187], v[192:195], v[122:125]
	v_mfma_f32_16x16x32_bf16 v[110:113], v[174:177], v[200:203], v[110:113]
	v_mfma_f32_16x16x32_bf16 v[106:109], v[184:187], v[200:203], v[106:109]
	v_mfma_f32_16x16x32_bf16 v[94:97], v[174:177], v[208:211], v[94:97]
	v_mfma_f32_16x16x32_bf16 v[90:93], v[184:187], v[208:211], v[90:93]
	v_mfma_f32_16x16x32_bf16 v[78:81], v[174:177], v[216:219], v[78:81]
	s_setprio 0
	v_mfma_f32_16x16x32_bf16 v[74:77], v[184:187], v[216:219], v[74:77]
	s_barrier
	s_add_i32 s51, s42, s30
	v_lshl_add_u64 v[220:221], s[26:27], 0, v[134:135]
	s_mov_b32 m0, s51
	ds_read_b128 v[188:191], v157 offset:16384
	ds_read_b128 v[192:195], v157 offset:17408
	ds_read_b128 v[196:199], v157 offset:18432
	ds_read_b128 v[200:203], v157 offset:19456
	ds_read_b128 v[204:207], v157 offset:20480
	ds_read_b128 v[208:211], v157 offset:21504
	ds_read_b128 v[212:215], v157 offset:22528
	ds_read_b128 v[216:219], v157 offset:23552
	global_load_lds_dwordx4 v[220:221], off
	s_add_i32 m0, s51, 0x2000
	s_add_u32 s56, s26, 0x40000
	v_lshl_add_u64 v[222:223], s[26:27], 0, v[130:131]
	s_addc_u32 s57, s27, 0
	s_add_i32 s51, s43, s30
	global_load_lds_dwordx4 v[222:223], off
	v_lshl_add_u64 v[224:225], s[56:57], 0, v[134:135]
	s_mov_b32 m0, s51
	v_lshl_add_u64 v[226:227], s[28:29], 0, v[132:133]
	global_load_lds_dwordx4 v[224:225], off
	v_lshl_add_u64 v[224:225], s[56:57], 0, v[130:131]
	s_add_i32 m0, s51, 0x2000
	s_nop 0
	global_load_lds_dwordx4 v[224:225], off
	v_lshl_add_u64 v[224:225], s[28:29], 0, v[136:137]
	s_mov_b32 m0, s23
	s_nop 0
	global_load_lds_dwordx4 v[224:225], off
	s_mov_b32 m0, s34
	s_nop 0
	global_load_lds_dwordx4 v[226:227], off
	s_waitcnt vmcnt(8)
	s_waitcnt lgkmcnt(0)
	s_setprio 1
	s_barrier
	v_mfma_f32_16x16x32_bf16 v[54:57], v[148:151], v[188:191], v[54:57]
	v_mfma_f32_16x16x32_bf16 v[50:53], v[162:165], v[188:191], v[50:53]
	v_mfma_f32_16x16x32_bf16 v[38:41], v[148:151], v[196:199], v[38:41]
	v_mfma_f32_16x16x32_bf16 v[34:37], v[162:165], v[196:199], v[34:37]
	v_mfma_f32_16x16x32_bf16 v[22:25], v[148:151], v[204:207], v[22:25]
	v_mfma_f32_16x16x32_bf16 v[18:21], v[162:165], v[204:207], v[18:21]
	v_mfma_f32_16x16x32_bf16 v[6:9], v[148:151], v[212:215], v[6:9]
	v_mfma_f32_16x16x32_bf16 v[2:5], v[162:165], v[212:215], v[2:5]
	v_mfma_f32_16x16x32_bf16 v[54:57], v[158:161], v[192:195], v[54:57]
	v_mfma_f32_16x16x32_bf16 v[50:53], v[166:169], v[192:195], v[50:53]
	v_mfma_f32_16x16x32_bf16 v[38:41], v[158:161], v[200:203], v[38:41]
	v_mfma_f32_16x16x32_bf16 v[34:37], v[166:169], v[200:203], v[34:37]
	v_mfma_f32_16x16x32_bf16 v[22:25], v[158:161], v[208:211], v[22:25]
	v_mfma_f32_16x16x32_bf16 v[18:21], v[166:169], v[208:211], v[18:21]
	v_mfma_f32_16x16x32_bf16 v[6:9], v[158:161], v[216:219], v[6:9]
	v_mfma_f32_16x16x32_bf16 v[2:5], v[166:169], v[216:219], v[2:5]
	v_mfma_f32_16x16x32_bf16 v[62:65], v[170:173], v[188:191], v[62:65]
	v_mfma_f32_16x16x32_bf16 v[58:61], v[180:183], v[188:191], v[58:61]
	v_mfma_f32_16x16x32_bf16 v[46:49], v[170:173], v[196:199], v[46:49]
	v_mfma_f32_16x16x32_bf16 v[42:45], v[180:183], v[196:199], v[42:45]
	v_mfma_f32_16x16x32_bf16 v[30:33], v[170:173], v[204:207], v[30:33]
	v_mfma_f32_16x16x32_bf16 v[26:29], v[180:183], v[204:207], v[26:29]
	v_mfma_f32_16x16x32_bf16 v[14:17], v[170:173], v[212:215], v[14:17]
	v_mfma_f32_16x16x32_bf16 v[10:13], v[180:183], v[212:215], v[10:13]
	v_mfma_f32_16x16x32_bf16 v[62:65], v[174:177], v[192:195], v[62:65]
	v_mfma_f32_16x16x32_bf16 v[58:61], v[184:187], v[192:195], v[58:61]
	v_mfma_f32_16x16x32_bf16 v[46:49], v[174:177], v[200:203], v[46:49]
	v_mfma_f32_16x16x32_bf16 v[42:45], v[184:187], v[200:203], v[42:45]
	v_mfma_f32_16x16x32_bf16 v[30:33], v[174:177], v[208:211], v[30:33]
	v_mfma_f32_16x16x32_bf16 v[26:29], v[184:187], v[208:211], v[26:29]
	v_mfma_f32_16x16x32_bf16 v[14:17], v[174:177], v[216:219], v[14:17]
	s_setprio 0
	v_mfma_f32_16x16x32_bf16 v[10:13], v[184:187], v[216:219], v[10:13]
	s_barrier
	s_add_i32 s51, 0, 0x18000
	s_add_i32 s56, 0, 0x1c000
	v_add_u32_e32 v166, s51, v153
	v_add_u32_e32 v179, s56, v153
	ds_read_b128 v[148:151], v166
	ds_read_b128 v[158:161], v166 offset:1024
	ds_read_b128 v[162:165], v166 offset:2048
	ds_read_b128 v[166:169], v166 offset:3072
	ds_read_b128 v[170:173], v179
	ds_read_b128 v[174:177], v179 offset:1024
	ds_read_b128 v[180:183], v179 offset:2048
	ds_read_b128 v[184:187], v179 offset:3072
	s_add_u32 s28, s28, 0x40000
	s_addc_u32 s29, s29, 0
	s_mov_b32 m0, s35
	v_lshl_add_u64 v[228:229], s[28:29], 0, v[136:137]
	ds_read_b128 v[188:191], v157 offset:32768
	ds_read_b128 v[192:195], v157 offset:33792
	ds_read_b128 v[196:199], v157 offset:34816
	ds_read_b128 v[200:203], v157 offset:35840
	ds_read_b128 v[204:207], v157 offset:36864
	ds_read_b128 v[208:211], v157 offset:37888
	ds_read_b128 v[212:215], v157 offset:38912
	ds_read_b128 v[216:219], v157 offset:39936
	global_load_lds_dwordx4 v[228:229], off
	v_lshl_add_u64 v[228:229], s[28:29], 0, v[132:133]
	s_mov_b32 m0, s36
	s_nop 0
	global_load_lds_dwordx4 v[228:229], off
	s_waitcnt vmcnt(8)
	s_waitcnt lgkmcnt(0)
	s_setprio 1
	s_barrier
	v_mfma_f32_16x16x32_bf16 v[118:121], v[148:151], v[188:191], v[118:121]
	v_mfma_f32_16x16x32_bf16 v[114:117], v[162:165], v[188:191], v[114:117]
	v_mfma_f32_16x16x32_bf16 v[102:105], v[148:151], v[196:199], v[102:105]
	v_mfma_f32_16x16x32_bf16 v[98:101], v[162:165], v[196:199], v[98:101]
	v_mfma_f32_16x16x32_bf16 v[86:89], v[148:151], v[204:207], v[86:89]
	v_mfma_f32_16x16x32_bf16 v[82:85], v[162:165], v[204:207], v[82:85]
	v_mfma_f32_16x16x32_bf16 v[70:73], v[148:151], v[212:215], v[70:73]
	v_mfma_f32_16x16x32_bf16 v[66:69], v[162:165], v[212:215], v[66:69]
	v_mfma_f32_16x16x32_bf16 v[118:121], v[158:161], v[192:195], v[118:121]
	v_mfma_f32_16x16x32_bf16 v[114:117], v[166:169], v[192:195], v[114:117]
	v_mfma_f32_16x16x32_bf16 v[102:105], v[158:161], v[200:203], v[102:105]
	v_mfma_f32_16x16x32_bf16 v[98:101], v[166:169], v[200:203], v[98:101]
	v_mfma_f32_16x16x32_bf16 v[86:89], v[158:161], v[208:211], v[86:89]
	v_mfma_f32_16x16x32_bf16 v[82:85], v[166:169], v[208:211], v[82:85]
	v_mfma_f32_16x16x32_bf16 v[70:73], v[158:161], v[216:219], v[70:73]
	v_mfma_f32_16x16x32_bf16 v[66:69], v[166:169], v[216:219], v[66:69]
	v_mfma_f32_16x16x32_bf16 v[126:129], v[170:173], v[188:191], v[126:129]
	v_mfma_f32_16x16x32_bf16 v[122:125], v[180:183], v[188:191], v[122:125]
	v_mfma_f32_16x16x32_bf16 v[110:113], v[170:173], v[196:199], v[110:113]
	v_mfma_f32_16x16x32_bf16 v[106:109], v[180:183], v[196:199], v[106:109]
	v_mfma_f32_16x16x32_bf16 v[94:97], v[170:173], v[204:207], v[94:97]
	v_mfma_f32_16x16x32_bf16 v[90:93], v[180:183], v[204:207], v[90:93]
	v_mfma_f32_16x16x32_bf16 v[78:81], v[170:173], v[212:215], v[78:81]
	v_mfma_f32_16x16x32_bf16 v[74:77], v[180:183], v[212:215], v[74:77]
	v_mfma_f32_16x16x32_bf16 v[126:129], v[174:177], v[192:195], v[126:129]
	v_mfma_f32_16x16x32_bf16 v[122:125], v[184:187], v[192:195], v[122:125]
	v_mfma_f32_16x16x32_bf16 v[110:113], v[174:177], v[200:203], v[110:113]
	v_mfma_f32_16x16x32_bf16 v[106:109], v[184:187], v[200:203], v[106:109]
	v_mfma_f32_16x16x32_bf16 v[94:97], v[174:177], v[208:211], v[94:97]
	v_mfma_f32_16x16x32_bf16 v[90:93], v[184:187], v[208:211], v[90:93]
	v_mfma_f32_16x16x32_bf16 v[78:81], v[174:177], v[216:219], v[78:81]
	s_setprio 0
	v_mfma_f32_16x16x32_bf16 v[74:77], v[184:187], v[216:219], v[74:77]
	s_barrier
	s_add_i32 s28, s51, s30
	v_lshl_add_u64 v[220:221], v[220:221], 0, s[2:3]
	s_mov_b32 m0, s28
	ds_read_b128 v[188:191], v157 offset:49152
	ds_read_b128 v[192:195], v157 offset:50176
	ds_read_b128 v[196:199], v157 offset:51200
	ds_read_b128 v[200:203], v157 offset:52224
	ds_read_b128 v[204:207], v157 offset:53248
	ds_read_b128 v[208:211], v157 offset:54272
	ds_read_b128 v[212:215], v157 offset:55296
	ds_read_b128 v[216:219], v157 offset:56320
	global_load_lds_dwordx4 v[220:221], off
	s_add_i32 m0, s28, 0x2000
	s_add_u32 s26, s26, 0x40080
	v_lshl_add_u64 v[220:221], v[222:223], 0, s[2:3]
	s_addc_u32 s27, s27, 0
	s_add_i32 s28, s56, s30
	global_load_lds_dwordx4 v[220:221], off
	v_lshl_add_u64 v[220:221], s[26:27], 0, v[134:135]
	s_mov_b32 m0, s28
	s_nop 0
	global_load_lds_dwordx4 v[220:221], off
	v_lshl_add_u64 v[220:221], s[26:27], 0, v[130:131]
	s_add_i32 m0, s28, 0x2000
	s_nop 0
	global_load_lds_dwordx4 v[220:221], off
	v_lshl_add_u64 v[220:221], v[224:225], 0, s[2:3]
	s_mov_b32 m0, s38
	s_nop 0
	global_load_lds_dwordx4 v[220:221], off
	v_lshl_add_u64 v[220:221], v[226:227], 0, s[2:3]
	s_mov_b32 m0, s39
	s_nop 0
	global_load_lds_dwordx4 v[220:221], off
	s_waitcnt vmcnt(8)
	s_waitcnt lgkmcnt(0)
	s_setprio 1
	s_barrier
	v_mfma_f32_16x16x32_bf16 v[54:57], v[148:151], v[188:191], v[54:57]
	v_mfma_f32_16x16x32_bf16 v[50:53], v[162:165], v[188:191], v[50:53]
	v_mfma_f32_16x16x32_bf16 v[38:41], v[148:151], v[196:199], v[38:41]
	v_mfma_f32_16x16x32_bf16 v[34:37], v[162:165], v[196:199], v[34:37]
	v_mfma_f32_16x16x32_bf16 v[22:25], v[148:151], v[204:207], v[22:25]
	v_mfma_f32_16x16x32_bf16 v[18:21], v[162:165], v[204:207], v[18:21]
	v_mfma_f32_16x16x32_bf16 v[6:9], v[148:151], v[212:215], v[6:9]
	v_mfma_f32_16x16x32_bf16 v[2:5], v[162:165], v[212:215], v[2:5]
	v_mfma_f32_16x16x32_bf16 v[54:57], v[158:161], v[192:195], v[54:57]
	v_mfma_f32_16x16x32_bf16 v[50:53], v[166:169], v[192:195], v[50:53]
	v_mfma_f32_16x16x32_bf16 v[38:41], v[158:161], v[200:203], v[38:41]
	v_mfma_f32_16x16x32_bf16 v[34:37], v[166:169], v[200:203], v[34:37]
	v_mfma_f32_16x16x32_bf16 v[22:25], v[158:161], v[208:211], v[22:25]
	v_mfma_f32_16x16x32_bf16 v[18:21], v[166:169], v[208:211], v[18:21]
	v_mfma_f32_16x16x32_bf16 v[6:9], v[158:161], v[216:219], v[6:9]
	v_mfma_f32_16x16x32_bf16 v[2:5], v[166:169], v[216:219], v[2:5]
	v_mfma_f32_16x16x32_bf16 v[62:65], v[170:173], v[188:191], v[62:65]
	v_mfma_f32_16x16x32_bf16 v[58:61], v[180:183], v[188:191], v[58:61]
	v_mfma_f32_16x16x32_bf16 v[46:49], v[170:173], v[196:199], v[46:49]
	v_mfma_f32_16x16x32_bf16 v[42:45], v[180:183], v[196:199], v[42:45]
	v_mfma_f32_16x16x32_bf16 v[30:33], v[170:173], v[204:207], v[30:33]
	v_mfma_f32_16x16x32_bf16 v[26:29], v[180:183], v[204:207], v[26:29]
	v_mfma_f32_16x16x32_bf16 v[14:17], v[170:173], v[212:215], v[14:17]
	v_mfma_f32_16x16x32_bf16 v[10:13], v[180:183], v[212:215], v[10:13]
	v_mfma_f32_16x16x32_bf16 v[62:65], v[174:177], v[192:195], v[62:65]
	v_mfma_f32_16x16x32_bf16 v[58:61], v[184:187], v[192:195], v[58:61]
	v_mfma_f32_16x16x32_bf16 v[46:49], v[174:177], v[200:203], v[46:49]
	v_mfma_f32_16x16x32_bf16 v[42:45], v[184:187], v[200:203], v[42:45]
	v_mfma_f32_16x16x32_bf16 v[30:33], v[174:177], v[208:211], v[30:33]
	v_mfma_f32_16x16x32_bf16 v[26:29], v[184:187], v[208:211], v[26:29]
	v_mfma_f32_16x16x32_bf16 v[14:17], v[174:177], v[216:219], v[14:17]
	s_setprio 0
	v_mfma_f32_16x16x32_bf16 v[10:13], v[184:187], v[216:219], v[10:13]
	s_barrier
	s_add_i32 s50, s50, 2
	s_add_u32 s24, s24, 0x100
	s_addc_u32 s25, s25, 0
	s_add_u32 s48, s48, 0x100
	s_addc_u32 s49, s49, 0
	s_cmp_gt_u32 s50, 13
	s_cbranch_scc0 .LBB0_1054
	s_and_b64 vcc, exec, s[8:9]
	s_cbranch_vccz .LBB0_1057
	s_barrier

.LBB0_1124:
	ds_read_b128 v[86:89], v182
	ds_read_b128 v[90:93], v182 offset:1024
	ds_read_b128 v[98:101], v182 offset:2048
	ds_read_b128 v[102:105], v182 offset:3072
	ds_read_b128 v[164:167], v183
	ds_read_b128 v[168:171], v183 offset:1024
	ds_read_b128 v[172:175], v183 offset:2048
	ds_read_b128 v[186:189], v183 offset:3072
	s_add_u32 s34, s30, 0xfff80080
	s_addc_u32 s35, s31, -1
	s_cmp_eq_u32 s59, 28
	s_cselect_b32 s37, s21, s35
	s_cselect_b32 s36, s27, s34
	s_cselect_b32 s35, s19, s58
	s_cselect_b32 s34, s29, s57
	v_lshl_add_u64 v[176:177], s[30:31], 0, v[156:157]
	s_add_i32 m0, s38, 0xc000
	ds_read_b128 v[190:193], v184
	ds_read_b128 v[194:197], v184 offset:1024
	ds_read_b128 v[198:201], v184 offset:2048
	ds_read_b128 v[202:205], v184 offset:3072
	ds_read_b128 v[206:209], v184 offset:4096
	ds_read_b128 v[210:213], v184 offset:5120
	ds_read_b128 v[214:217], v184 offset:6144
	ds_read_b128 v[218:221], v184 offset:7168
	global_load_lds_dwordx4 v[176:177], off
	v_lshl_add_u64 v[176:177], s[30:31], 0, v[158:159]
	s_add_i32 m0, s38, 0xe000
	s_nop 0
	global_load_lds_dwordx4 v[176:177], off
	s_waitcnt vmcnt(8)
	s_waitcnt lgkmcnt(0)
	s_setprio 1
	s_barrier
	v_mfma_f32_16x16x32_bf16 v[142:145], v[86:89], v[190:193], v[142:145]
	v_mfma_f32_16x16x32_bf16 v[138:141], v[98:101], v[190:193], v[138:141]
	v_mfma_f32_16x16x32_bf16 v[126:129], v[86:89], v[198:201], v[126:129]
	v_mfma_f32_16x16x32_bf16 v[122:125], v[98:101], v[198:201], v[122:125]
	v_mfma_f32_16x16x32_bf16 v[110:113], v[86:89], v[206:209], v[110:113]
	v_mfma_f32_16x16x32_bf16 v[106:109], v[98:101], v[206:209], v[106:109]
	v_mfma_f32_16x16x32_bf16 v[78:81], v[86:89], v[214:217], v[78:81]
	v_mfma_f32_16x16x32_bf16 v[74:77], v[98:101], v[214:217], v[74:77]
	v_mfma_f32_16x16x32_bf16 v[142:145], v[90:93], v[194:197], v[142:145]
	v_mfma_f32_16x16x32_bf16 v[138:141], v[102:105], v[194:197], v[138:141]
	v_mfma_f32_16x16x32_bf16 v[126:129], v[90:93], v[202:205], v[126:129]
	v_mfma_f32_16x16x32_bf16 v[122:125], v[102:105], v[202:205], v[122:125]
	v_mfma_f32_16x16x32_bf16 v[110:113], v[90:93], v[210:213], v[110:113]
	v_mfma_f32_16x16x32_bf16 v[106:109], v[102:105], v[210:213], v[106:109]
	v_mfma_f32_16x16x32_bf16 v[78:81], v[90:93], v[218:221], v[78:81]
	v_mfma_f32_16x16x32_bf16 v[74:77], v[102:105], v[218:221], v[74:77]
	v_mfma_f32_16x16x32_bf16 v[134:137], v[164:167], v[190:193], v[134:137]
	v_mfma_f32_16x16x32_bf16 v[130:133], v[172:175], v[190:193], v[130:133]
	v_mfma_f32_16x16x32_bf16 v[118:121], v[164:167], v[198:201], v[118:121]
	v_mfma_f32_16x16x32_bf16 v[114:117], v[172:175], v[198:201], v[114:117]
	v_mfma_f32_16x16x32_bf16 v[94:97], v[164:167], v[206:209], v[94:97]
	v_mfma_f32_16x16x32_bf16 v[82:85], v[172:175], v[206:209], v[82:85]
	v_mfma_f32_16x16x32_bf16 v[70:73], v[164:167], v[214:217], v[70:73]
	v_mfma_f32_16x16x32_bf16 v[66:69], v[172:175], v[214:217], v[66:69]
	v_mfma_f32_16x16x32_bf16 v[134:137], v[168:171], v[194:197], v[134:137]
	v_mfma_f32_16x16x32_bf16 v[130:133], v[186:189], v[194:197], v[130:133]
	v_mfma_f32_16x16x32_bf16 v[118:121], v[168:171], v[202:205], v[118:121]
	v_mfma_f32_16x16x32_bf16 v[114:117], v[186:189], v[202:205], v[114:117]
	v_mfma_f32_16x16x32_bf16 v[94:97], v[168:171], v[210:213], v[94:97]
	v_mfma_f32_16x16x32_bf16 v[82:85], v[186:189], v[210:213], v[82:85]
	v_mfma_f32_16x16x32_bf16 v[70:73], v[168:171], v[218:221], v[70:73]
	s_setprio 0
	v_mfma_f32_16x16x32_bf16 v[66:69], v[186:189], v[218:221], v[66:69]
	s_barrier
	s_add_i32 s68, s51, s33
	v_lshl_add_u64 v[176:177], s[34:35], 0, v[150:151]
	s_mov_b32 m0, s68
	ds_read_b128 v[190:193], v184 offset:16384
	ds_read_b128 v[194:197], v184 offset:17408
	ds_read_b128 v[198:201], v184 offset:18432
	ds_read_b128 v[202:205], v184 offset:19456
	ds_read_b128 v[206:209], v184 offset:20480
	ds_read_b128 v[210:213], v184 offset:21504
	ds_read_b128 v[214:217], v184 offset:22528
	ds_read_b128 v[218:221], v184 offset:23552
	global_load_lds_dwordx4 v[176:177], off
	s_add_i32 m0, s68, 0x2000
	s_add_u32 s68, s34, 0x80000
	v_lshl_add_u64 v[222:223], s[34:35], 0, v[154:155]
	s_addc_u32 s69, s35, 0
	s_add_i32 s70, s56, s33
	global_load_lds_dwordx4 v[222:223], off
	v_lshl_add_u64 v[224:225], s[68:69], 0, v[150:151]
	s_mov_b32 m0, s70
	v_lshl_add_u64 v[226:227], s[36:37], 0, v[152:153]
	global_load_lds_dwordx4 v[224:225], off
	v_lshl_add_u64 v[224:225], s[68:69], 0, v[154:155]
	s_add_i32 m0, s70, 0x2000
	s_nop 0
	global_load_lds_dwordx4 v[224:225], off
	v_lshl_add_u64 v[224:225], s[36:37], 0, v[148:149]
	s_mov_b32 m0, s38
	s_nop 0
	global_load_lds_dwordx4 v[224:225], off
	s_mov_b32 m0, s39
	s_nop 0
	global_load_lds_dwordx4 v[226:227], off
	s_waitcnt vmcnt(8)
	s_waitcnt lgkmcnt(0)
	s_setprio 1
	s_barrier
	v_mfma_f32_16x16x32_bf16 v[62:65], v[86:89], v[190:193], v[62:65]
	v_mfma_f32_16x16x32_bf16 v[58:61], v[98:101], v[190:193], v[58:61]
	v_mfma_f32_16x16x32_bf16 v[46:49], v[86:89], v[198:201], v[46:49]
	v_mfma_f32_16x16x32_bf16 v[42:45], v[98:101], v[198:201], v[42:45]
	v_mfma_f32_16x16x32_bf16 v[30:33], v[86:89], v[206:209], v[30:33]
	v_mfma_f32_16x16x32_bf16 v[26:29], v[98:101], v[206:209], v[26:29]
	v_mfma_f32_16x16x32_bf16 v[14:17], v[86:89], v[214:217], v[14:17]
	v_mfma_f32_16x16x32_bf16 v[10:13], v[98:101], v[214:217], v[10:13]
	v_mfma_f32_16x16x32_bf16 v[62:65], v[90:93], v[194:197], v[62:65]
	v_mfma_f32_16x16x32_bf16 v[58:61], v[102:105], v[194:197], v[58:61]
	v_mfma_f32_16x16x32_bf16 v[46:49], v[90:93], v[202:205], v[46:49]
	v_mfma_f32_16x16x32_bf16 v[42:45], v[102:105], v[202:205], v[42:45]
	v_mfma_f32_16x16x32_bf16 v[30:33], v[90:93], v[210:213], v[30:33]
	v_mfma_f32_16x16x32_bf16 v[26:29], v[102:105], v[210:213], v[26:29]
	v_mfma_f32_16x16x32_bf16 v[14:17], v[90:93], v[218:221], v[14:17]
	v_mfma_f32_16x16x32_bf16 v[10:13], v[102:105], v[218:221], v[10:13]
	v_mfma_f32_16x16x32_bf16 v[54:57], v[164:167], v[190:193], v[54:57]
	v_mfma_f32_16x16x32_bf16 v[50:53], v[172:175], v[190:193], v[50:53]
	v_mfma_f32_16x16x32_bf16 v[38:41], v[164:167], v[198:201], v[38:41]
	v_mfma_f32_16x16x32_bf16 v[34:37], v[172:175], v[198:201], v[34:37]
	v_mfma_f32_16x16x32_bf16 v[22:25], v[164:167], v[206:209], v[22:25]
	v_mfma_f32_16x16x32_bf16 v[18:21], v[172:175], v[206:209], v[18:21]
	v_mfma_f32_16x16x32_bf16 v[6:9], v[164:167], v[214:217], v[6:9]
	v_mfma_f32_16x16x32_bf16 v[2:5], v[172:175], v[214:217], v[2:5]
	v_mfma_f32_16x16x32_bf16 v[54:57], v[168:171], v[194:197], v[54:57]
	v_mfma_f32_16x16x32_bf16 v[50:53], v[186:189], v[194:197], v[50:53]
	v_mfma_f32_16x16x32_bf16 v[38:41], v[168:171], v[202:205], v[38:41]
	v_mfma_f32_16x16x32_bf16 v[34:37], v[186:189], v[202:205], v[34:37]
	v_mfma_f32_16x16x32_bf16 v[22:25], v[168:171], v[210:213], v[22:25]
	v_mfma_f32_16x16x32_bf16 v[18:21], v[186:189], v[210:213], v[18:21]
	v_mfma_f32_16x16x32_bf16 v[6:9], v[168:171], v[218:221], v[6:9]
	s_setprio 0
	v_mfma_f32_16x16x32_bf16 v[2:5], v[186:189], v[218:221], v[2:5]
	s_barrier
	s_add_i32 s68, 0, 0x18000
	s_add_i32 s69, 0, 0x1c000
	v_add_u32_e32 v102, s68, v180
	v_add_u32_e32 v185, s69, v180
	ds_read_b128 v[86:89], v102
	ds_read_b128 v[90:93], v102 offset:1024
	ds_read_b128 v[98:101], v102 offset:2048
	ds_read_b128 v[102:105], v102 offset:3072
	ds_read_b128 v[164:167], v185
	ds_read_b128 v[168:171], v185 offset:1024
	ds_read_b128 v[172:175], v185 offset:2048
	ds_read_b128 v[186:189], v185 offset:3072
	s_add_u32 s36, s36, 0x80000
	s_addc_u32 s37, s37, 0
	s_mov_b32 m0, s40
	v_lshl_add_u64 v[228:229], s[36:37], 0, v[148:149]
	ds_read_b128 v[190:193], v184 offset:32768
	ds_read_b128 v[194:197], v184 offset:33792
	ds_read_b128 v[198:201], v184 offset:34816
	ds_read_b128 v[202:205], v184 offset:35840
	ds_read_b128 v[206:209], v184 offset:36864
	ds_read_b128 v[210:213], v184 offset:37888
	ds_read_b128 v[214:217], v184 offset:38912
	ds_read_b128 v[218:221], v184 offset:39936
	global_load_lds_dwordx4 v[228:229], off
	v_lshl_add_u64 v[228:229], s[36:37], 0, v[152:153]
	s_mov_b32 m0, s41
	s_nop 0
	global_load_lds_dwordx4 v[228:229], off
	s_waitcnt vmcnt(8)
	s_waitcnt lgkmcnt(0)
	s_setprio 1
	s_barrier
	v_mfma_f32_16x16x32_bf16 v[142:145], v[86:89], v[190:193], v[142:145]
	v_mfma_f32_16x16x32_bf16 v[138:141], v[98:101], v[190:193], v[138:141]
	v_mfma_f32_16x16x32_bf16 v[126:129], v[86:89], v[198:201], v[126:129]
	v_mfma_f32_16x16x32_bf16 v[122:125], v[98:101], v[198:201], v[122:125]
	v_mfma_f32_16x16x32_bf16 v[110:113], v[86:89], v[206:209], v[110:113]
	v_mfma_f32_16x16x32_bf16 v[106:109], v[98:101], v[206:209], v[106:109]
	v_mfma_f32_16x16x32_bf16 v[78:81], v[86:89], v[214:217], v[78:81]
	v_mfma_f32_16x16x32_bf16 v[74:77], v[98:101], v[214:217], v[74:77]
	v_mfma_f32_16x16x32_bf16 v[142:145], v[90:93], v[194:197], v[142:145]
	v_mfma_f32_16x16x32_bf16 v[138:141], v[102:105], v[194:197], v[138:141]
	v_mfma_f32_16x16x32_bf16 v[126:129], v[90:93], v[202:205], v[126:129]
	v_mfma_f32_16x16x32_bf16 v[122:125], v[102:105], v[202:205], v[122:125]
	v_mfma_f32_16x16x32_bf16 v[110:113], v[90:93], v[210:213], v[110:113]
	v_mfma_f32_16x16x32_bf16 v[106:109], v[102:105], v[210:213], v[106:109]
	v_mfma_f32_16x16x32_bf16 v[78:81], v[90:93], v[218:221], v[78:81]
	v_mfma_f32_16x16x32_bf16 v[74:77], v[102:105], v[218:221], v[74:77]
	v_mfma_f32_16x16x32_bf16 v[134:137], v[164:167], v[190:193], v[134:137]
	v_mfma_f32_16x16x32_bf16 v[130:133], v[172:175], v[190:193], v[130:133]
	v_mfma_f32_16x16x32_bf16 v[118:121], v[164:167], v[198:201], v[118:121]
	v_mfma_f32_16x16x32_bf16 v[114:117], v[172:175], v[198:201], v[114:117]
	v_mfma_f32_16x16x32_bf16 v[94:97], v[164:167], v[206:209], v[94:97]
	v_mfma_f32_16x16x32_bf16 v[82:85], v[172:175], v[206:209], v[82:85]
	v_mfma_f32_16x16x32_bf16 v[70:73], v[164:167], v[214:217], v[70:73]
	v_mfma_f32_16x16x32_bf16 v[66:69], v[172:175], v[214:217], v[66:69]
	v_mfma_f32_16x16x32_bf16 v[134:137], v[168:171], v[194:197], v[134:137]
	v_mfma_f32_16x16x32_bf16 v[130:133], v[186:189], v[194:197], v[130:133]
	v_mfma_f32_16x16x32_bf16 v[118:121], v[168:171], v[202:205], v[118:121]
	v_mfma_f32_16x16x32_bf16 v[114:117], v[186:189], v[202:205], v[114:117]
	v_mfma_f32_16x16x32_bf16 v[94:97], v[168:171], v[210:213], v[94:97]
	v_mfma_f32_16x16x32_bf16 v[82:85], v[186:189], v[210:213], v[82:85]
	v_mfma_f32_16x16x32_bf16 v[70:73], v[168:171], v[218:221], v[70:73]
	s_setprio 0
	v_mfma_f32_16x16x32_bf16 v[66:69], v[186:189], v[218:221], v[66:69]
	s_barrier
	s_add_i32 s36, s68, s33
	v_lshl_add_u64 v[176:177], v[176:177], 0, s[2:3]
	s_mov_b32 m0, s36
	ds_read_b128 v[190:193], v184 offset:49152
	ds_read_b128 v[194:197], v184 offset:50176
	ds_read_b128 v[198:201], v184 offset:51200
	ds_read_b128 v[202:205], v184 offset:52224
	ds_read_b128 v[206:209], v184 offset:53248
	ds_read_b128 v[210:213], v184 offset:54272
	ds_read_b128 v[214:217], v184 offset:55296
	ds_read_b128 v[218:221], v184 offset:56320
	global_load_lds_dwordx4 v[176:177], off
	s_add_i32 m0, s36, 0x2000
	s_add_u32 s34, s34, 0x80080
	v_lshl_add_u64 v[176:177], v[222:223], 0, s[2:3]
	s_addc_u32 s35, s35, 0
	s_add_i32 s36, s69, s33
	global_load_lds_dwordx4 v[176:177], off
	v_lshl_add_u64 v[176:177], s[34:35], 0, v[150:151]
	s_mov_b32 m0, s36
	s_nop 0
	global_load_lds_dwordx4 v[176:177], off
	v_lshl_add_u64 v[176:177], s[34:35], 0, v[154:155]
	s_add_i32 m0, s36, 0x2000
	s_nop 0
	global_load_lds_dwordx4 v[176:177], off
	v_lshl_add_u64 v[176:177], v[224:225], 0, s[2:3]
	s_mov_b32 m0, s43
	s_nop 0
	global_load_lds_dwordx4 v[176:177], off
	v_lshl_add_u64 v[176:177], v[226:227], 0, s[2:3]
	s_mov_b32 m0, s44
	s_nop 0
	global_load_lds_dwordx4 v[176:177], off
	s_waitcnt vmcnt(8)
	s_waitcnt lgkmcnt(0)
	s_setprio 1
	s_barrier
	v_mfma_f32_16x16x32_bf16 v[62:65], v[86:89], v[190:193], v[62:65]
	v_mfma_f32_16x16x32_bf16 v[58:61], v[98:101], v[190:193], v[58:61]
	v_mfma_f32_16x16x32_bf16 v[46:49], v[86:89], v[198:201], v[46:49]
	v_mfma_f32_16x16x32_bf16 v[42:45], v[98:101], v[198:201], v[42:45]
	v_mfma_f32_16x16x32_bf16 v[30:33], v[86:89], v[206:209], v[30:33]
	v_mfma_f32_16x16x32_bf16 v[26:29], v[98:101], v[206:209], v[26:29]
	v_mfma_f32_16x16x32_bf16 v[14:17], v[86:89], v[214:217], v[14:17]
	v_mfma_f32_16x16x32_bf16 v[10:13], v[98:101], v[214:217], v[10:13]
	v_mfma_f32_16x16x32_bf16 v[62:65], v[90:93], v[194:197], v[62:65]
	v_mfma_f32_16x16x32_bf16 v[58:61], v[102:105], v[194:197], v[58:61]
	v_mfma_f32_16x16x32_bf16 v[46:49], v[90:93], v[202:205], v[46:49]
	v_mfma_f32_16x16x32_bf16 v[42:45], v[102:105], v[202:205], v[42:45]
	v_mfma_f32_16x16x32_bf16 v[30:33], v[90:93], v[210:213], v[30:33]
	v_mfma_f32_16x16x32_bf16 v[26:29], v[102:105], v[210:213], v[26:29]
	v_mfma_f32_16x16x32_bf16 v[14:17], v[90:93], v[218:221], v[14:17]
	v_mfma_f32_16x16x32_bf16 v[10:13], v[102:105], v[218:221], v[10:13]
	v_mfma_f32_16x16x32_bf16 v[54:57], v[164:167], v[190:193], v[54:57]
	v_mfma_f32_16x16x32_bf16 v[50:53], v[172:175], v[190:193], v[50:53]
	v_mfma_f32_16x16x32_bf16 v[38:41], v[164:167], v[198:201], v[38:41]
	v_mfma_f32_16x16x32_bf16 v[34:37], v[172:175], v[198:201], v[34:37]
	v_mfma_f32_16x16x32_bf16 v[22:25], v[164:167], v[206:209], v[22:25]
	v_mfma_f32_16x16x32_bf16 v[18:21], v[172:175], v[206:209], v[18:21]
	v_mfma_f32_16x16x32_bf16 v[6:9], v[164:167], v[214:217], v[6:9]
	v_mfma_f32_16x16x32_bf16 v[2:5], v[172:175], v[214:217], v[2:5]
	v_mfma_f32_16x16x32_bf16 v[54:57], v[168:171], v[194:197], v[54:57]
	v_mfma_f32_16x16x32_bf16 v[50:53], v[186:189], v[194:197], v[50:53]
	v_mfma_f32_16x16x32_bf16 v[38:41], v[168:171], v[202:205], v[38:41]
	v_mfma_f32_16x16x32_bf16 v[34:37], v[186:189], v[202:205], v[34:37]
	v_mfma_f32_16x16x32_bf16 v[22:25], v[168:171], v[210:213], v[22:25]
	v_mfma_f32_16x16x32_bf16 v[18:21], v[186:189], v[210:213], v[18:21]
	v_mfma_f32_16x16x32_bf16 v[6:9], v[168:171], v[218:221], v[6:9]
	s_setprio 0
	v_mfma_f32_16x16x32_bf16 v[2:5], v[186:189], v[218:221], v[2:5]
	s_barrier
	s_add_i32 s59, s59, 2
	s_add_u32 s30, s30, 0x100
	s_addc_u32 s31, s31, 0
	s_add_u32 s57, s57, 0x100
	s_addc_u32 s58, s58, 0
	s_cmp_gt_u32 s59, 29
	s_cbranch_scc0 .LBB0_1124
	s_and_b64 vcc, exec, s[16:17]
	s_cbranch_vccz .LBB0_1127
	s_barrier

.LBB0_1208:
	ds_read_b128 v[98:101], v175
	ds_read_b128 v[102:105], v175 offset:1024
	ds_read_b128 v[106:109], v175 offset:2048
	ds_read_b128 v[110:113], v175 offset:3072
	ds_read_b128 v[164:167], v176
	ds_read_b128 v[168:171], v176 offset:1024
	ds_read_b128 v[182:185], v176 offset:2048
	ds_read_b128 v[186:189], v176 offset:3072
	s_add_u32 s28, s26, 0xfff80080
	s_addc_u32 s29, s27, -1
	s_cmp_eq_u32 s58, 28
	s_cselect_b32 s31, s21, s29
	s_cselect_b32 s30, s50, s28
	s_cselect_b32 s29, s19, s57
	s_cselect_b32 s28, s51, s56
	v_lshl_add_u64 v[222:223], s[26:27], 0, v[156:157]
	s_add_i32 m0, s36, 0xc000
	ds_read_b128 v[190:193], v177
	ds_read_b128 v[194:197], v177 offset:1024
	ds_read_b128 v[198:201], v177 offset:2048
	ds_read_b128 v[202:205], v177 offset:3072
	ds_read_b128 v[206:209], v177 offset:4096
	ds_read_b128 v[210:213], v177 offset:5120
	ds_read_b128 v[214:217], v177 offset:6144
	ds_read_b128 v[218:221], v177 offset:7168
	global_load_lds_dwordx4 v[222:223], off
	v_lshl_add_u64 v[222:223], s[26:27], 0, v[158:159]
	s_add_i32 m0, s36, 0xe000
	s_nop 0
	global_load_lds_dwordx4 v[222:223], off
	s_waitcnt vmcnt(8)
	s_waitcnt lgkmcnt(0)
	s_setprio 1
	s_barrier
	v_mfma_f32_16x16x32_bf16 v[142:145], v[98:101], v[190:193], v[142:145]
	v_mfma_f32_16x16x32_bf16 v[138:141], v[106:109], v[190:193], v[138:141]
	v_mfma_f32_16x16x32_bf16 v[126:129], v[98:101], v[198:201], v[126:129]
	v_mfma_f32_16x16x32_bf16 v[122:125], v[106:109], v[198:201], v[122:125]
	v_mfma_f32_16x16x32_bf16 v[94:97], v[98:101], v[206:209], v[94:97]
	v_mfma_f32_16x16x32_bf16 v[90:93], v[106:109], v[206:209], v[90:93]
	v_mfma_f32_16x16x32_bf16 v[78:81], v[98:101], v[214:217], v[78:81]
	v_mfma_f32_16x16x32_bf16 v[74:77], v[106:109], v[214:217], v[74:77]
	v_mfma_f32_16x16x32_bf16 v[142:145], v[102:105], v[194:197], v[142:145]
	v_mfma_f32_16x16x32_bf16 v[138:141], v[110:113], v[194:197], v[138:141]
	v_mfma_f32_16x16x32_bf16 v[126:129], v[102:105], v[202:205], v[126:129]
	v_mfma_f32_16x16x32_bf16 v[122:125], v[110:113], v[202:205], v[122:125]
	v_mfma_f32_16x16x32_bf16 v[94:97], v[102:105], v[210:213], v[94:97]
	v_mfma_f32_16x16x32_bf16 v[90:93], v[110:113], v[210:213], v[90:93]
	v_mfma_f32_16x16x32_bf16 v[78:81], v[102:105], v[218:221], v[78:81]
	v_mfma_f32_16x16x32_bf16 v[74:77], v[110:113], v[218:221], v[74:77]
	v_mfma_f32_16x16x32_bf16 v[134:137], v[164:167], v[190:193], v[134:137]
	v_mfma_f32_16x16x32_bf16 v[130:133], v[182:185], v[190:193], v[130:133]
	v_mfma_f32_16x16x32_bf16 v[118:121], v[164:167], v[198:201], v[118:121]
	v_mfma_f32_16x16x32_bf16 v[114:117], v[182:185], v[198:201], v[114:117]
	v_mfma_f32_16x16x32_bf16 v[86:89], v[164:167], v[206:209], v[86:89]
	v_mfma_f32_16x16x32_bf16 v[82:85], v[182:185], v[206:209], v[82:85]
	v_mfma_f32_16x16x32_bf16 v[70:73], v[164:167], v[214:217], v[70:73]
	v_mfma_f32_16x16x32_bf16 v[66:69], v[182:185], v[214:217], v[66:69]
	v_mfma_f32_16x16x32_bf16 v[134:137], v[168:171], v[194:197], v[134:137]
	v_mfma_f32_16x16x32_bf16 v[130:133], v[186:189], v[194:197], v[130:133]
	v_mfma_f32_16x16x32_bf16 v[118:121], v[168:171], v[202:205], v[118:121]
	v_mfma_f32_16x16x32_bf16 v[114:117], v[186:189], v[202:205], v[114:117]
	v_mfma_f32_16x16x32_bf16 v[86:89], v[168:171], v[210:213], v[86:89]
	v_mfma_f32_16x16x32_bf16 v[82:85], v[186:189], v[210:213], v[82:85]
	v_mfma_f32_16x16x32_bf16 v[70:73], v[168:171], v[218:221], v[70:73]
	s_setprio 0
	v_mfma_f32_16x16x32_bf16 v[66:69], v[186:189], v[218:221], v[66:69]
	s_barrier
	s_add_i32 s59, s45, s33
	v_lshl_add_u64 v[222:223], s[28:29], 0, v[152:153]
	s_mov_b32 m0, s59
	ds_read_b128 v[190:193], v177 offset:16384
	ds_read_b128 v[194:197], v177 offset:17408
	ds_read_b128 v[198:201], v177 offset:18432
	ds_read_b128 v[202:205], v177 offset:19456
	ds_read_b128 v[206:209], v177 offset:20480
	ds_read_b128 v[210:213], v177 offset:21504
	ds_read_b128 v[214:217], v177 offset:22528
	ds_read_b128 v[218:221], v177 offset:23552
	global_load_lds_dwordx4 v[222:223], off
	s_add_i32 m0, s59, 0x2000
	s_add_u32 s68, s28, 0x80000
	v_lshl_add_u64 v[224:225], s[28:29], 0, v[148:149]
	s_addc_u32 s69, s29, 0
	s_add_i32 s59, s46, s33
	global_load_lds_dwordx4 v[224:225], off
	v_lshl_add_u64 v[226:227], s[68:69], 0, v[152:153]
	s_mov_b32 m0, s59
	v_lshl_add_u64 v[228:229], s[30:31], 0, v[150:151]
	global_load_lds_dwordx4 v[226:227], off
	v_lshl_add_u64 v[226:227], s[68:69], 0, v[148:149]
	s_add_i32 m0, s59, 0x2000
	s_nop 0
	global_load_lds_dwordx4 v[226:227], off
	v_lshl_add_u64 v[226:227], s[30:31], 0, v[154:155]
	s_mov_b32 m0, s36
	s_nop 0
	global_load_lds_dwordx4 v[226:227], off
	s_mov_b32 m0, s37
	s_nop 0
	global_load_lds_dwordx4 v[228:229], off
	s_waitcnt vmcnt(8)
	s_waitcnt lgkmcnt(0)
	s_setprio 1
	s_barrier
	v_mfma_f32_16x16x32_bf16 v[62:65], v[98:101], v[190:193], v[62:65]
	v_mfma_f32_16x16x32_bf16 v[58:61], v[106:109], v[190:193], v[58:61]
	v_mfma_f32_16x16x32_bf16 v[46:49], v[98:101], v[198:201], v[46:49]
	v_mfma_f32_16x16x32_bf16 v[42:45], v[106:109], v[198:201], v[42:45]
	v_mfma_f32_16x16x32_bf16 v[30:33], v[98:101], v[206:209], v[30:33]
	v_mfma_f32_16x16x32_bf16 v[26:29], v[106:109], v[206:209], v[26:29]
	v_mfma_f32_16x16x32_bf16 v[14:17], v[98:101], v[214:217], v[14:17]
	v_mfma_f32_16x16x32_bf16 v[10:13], v[106:109], v[214:217], v[10:13]
	v_mfma_f32_16x16x32_bf16 v[62:65], v[102:105], v[194:197], v[62:65]
	v_mfma_f32_16x16x32_bf16 v[58:61], v[110:113], v[194:197], v[58:61]
	v_mfma_f32_16x16x32_bf16 v[46:49], v[102:105], v[202:205], v[46:49]
	v_mfma_f32_16x16x32_bf16 v[42:45], v[110:113], v[202:205], v[42:45]
	v_mfma_f32_16x16x32_bf16 v[30:33], v[102:105], v[210:213], v[30:33]
	v_mfma_f32_16x16x32_bf16 v[26:29], v[110:113], v[210:213], v[26:29]
	v_mfma_f32_16x16x32_bf16 v[14:17], v[102:105], v[218:221], v[14:17]
	v_mfma_f32_16x16x32_bf16 v[10:13], v[110:113], v[218:221], v[10:13]
	v_mfma_f32_16x16x32_bf16 v[54:57], v[164:167], v[190:193], v[54:57]
	v_mfma_f32_16x16x32_bf16 v[50:53], v[182:185], v[190:193], v[50:53]
	v_mfma_f32_16x16x32_bf16 v[38:41], v[164:167], v[198:201], v[38:41]
	v_mfma_f32_16x16x32_bf16 v[34:37], v[182:185], v[198:201], v[34:37]
	v_mfma_f32_16x16x32_bf16 v[22:25], v[164:167], v[206:209], v[22:25]
	v_mfma_f32_16x16x32_bf16 v[18:21], v[182:185], v[206:209], v[18:21]
	v_mfma_f32_16x16x32_bf16 v[6:9], v[164:167], v[214:217], v[6:9]
	v_mfma_f32_16x16x32_bf16 v[2:5], v[182:185], v[214:217], v[2:5]
	v_mfma_f32_16x16x32_bf16 v[54:57], v[168:171], v[194:197], v[54:57]
	v_mfma_f32_16x16x32_bf16 v[50:53], v[186:189], v[194:197], v[50:53]
	v_mfma_f32_16x16x32_bf16 v[38:41], v[168:171], v[202:205], v[38:41]
	v_mfma_f32_16x16x32_bf16 v[34:37], v[186:189], v[202:205], v[34:37]
	v_mfma_f32_16x16x32_bf16 v[22:25], v[168:171], v[210:213], v[22:25]
	v_mfma_f32_16x16x32_bf16 v[18:21], v[186:189], v[210:213], v[18:21]
	v_mfma_f32_16x16x32_bf16 v[6:9], v[168:171], v[218:221], v[6:9]
	s_setprio 0
	v_mfma_f32_16x16x32_bf16 v[2:5], v[186:189], v[218:221], v[2:5]
	s_barrier
	s_add_i32 s59, 0, 0x18000
	s_add_i32 s68, 0, 0x1c000
	v_add_u32_e32 v110, s59, v173
	v_add_u32_e32 v181, s68, v173
	ds_read_b128 v[98:101], v110
	ds_read_b128 v[102:105], v110 offset:1024
	ds_read_b128 v[106:109], v110 offset:2048
	ds_read_b128 v[110:113], v110 offset:3072
	ds_read_b128 v[164:167], v181
	ds_read_b128 v[168:171], v181 offset:1024
	ds_read_b128 v[182:185], v181 offset:2048
	ds_read_b128 v[186:189], v181 offset:3072
	s_add_u32 s30, s30, 0x80000
	s_addc_u32 s31, s31, 0
	s_mov_b32 m0, s38
	v_lshl_add_u64 v[230:231], s[30:31], 0, v[154:155]
	ds_read_b128 v[190:193], v177 offset:32768
	ds_read_b128 v[194:197], v177 offset:33792
	ds_read_b128 v[198:201], v177 offset:34816
	ds_read_b128 v[202:205], v177 offset:35840
	ds_read_b128 v[206:209], v177 offset:36864
	ds_read_b128 v[210:213], v177 offset:37888
	ds_read_b128 v[214:217], v177 offset:38912
	ds_read_b128 v[218:221], v177 offset:39936
	global_load_lds_dwordx4 v[230:231], off
	v_lshl_add_u64 v[230:231], s[30:31], 0, v[150:151]
	s_mov_b32 m0, s39
	s_nop 0
	global_load_lds_dwordx4 v[230:231], off
	s_waitcnt vmcnt(8)
	s_waitcnt lgkmcnt(0)
	s_setprio 1
	s_barrier
	v_mfma_f32_16x16x32_bf16 v[142:145], v[98:101], v[190:193], v[142:145]
	v_mfma_f32_16x16x32_bf16 v[138:141], v[106:109], v[190:193], v[138:141]
	v_mfma_f32_16x16x32_bf16 v[126:129], v[98:101], v[198:201], v[126:129]
	v_mfma_f32_16x16x32_bf16 v[122:125], v[106:109], v[198:201], v[122:125]
	v_mfma_f32_16x16x32_bf16 v[94:97], v[98:101], v[206:209], v[94:97]
	v_mfma_f32_16x16x32_bf16 v[90:93], v[106:109], v[206:209], v[90:93]
	v_mfma_f32_16x16x32_bf16 v[78:81], v[98:101], v[214:217], v[78:81]
	v_mfma_f32_16x16x32_bf16 v[74:77], v[106:109], v[214:217], v[74:77]
	v_mfma_f32_16x16x32_bf16 v[142:145], v[102:105], v[194:197], v[142:145]
	v_mfma_f32_16x16x32_bf16 v[138:141], v[110:113], v[194:197], v[138:141]
	v_mfma_f32_16x16x32_bf16 v[126:129], v[102:105], v[202:205], v[126:129]
	v_mfma_f32_16x16x32_bf16 v[122:125], v[110:113], v[202:205], v[122:125]
	v_mfma_f32_16x16x32_bf16 v[94:97], v[102:105], v[210:213], v[94:97]
	v_mfma_f32_16x16x32_bf16 v[90:93], v[110:113], v[210:213], v[90:93]
	v_mfma_f32_16x16x32_bf16 v[78:81], v[102:105], v[218:221], v[78:81]
	v_mfma_f32_16x16x32_bf16 v[74:77], v[110:113], v[218:221], v[74:77]
	v_mfma_f32_16x16x32_bf16 v[134:137], v[164:167], v[190:193], v[134:137]
	v_mfma_f32_16x16x32_bf16 v[130:133], v[182:185], v[190:193], v[130:133]
	v_mfma_f32_16x16x32_bf16 v[118:121], v[164:167], v[198:201], v[118:121]
	v_mfma_f32_16x16x32_bf16 v[114:117], v[182:185], v[198:201], v[114:117]
	v_mfma_f32_16x16x32_bf16 v[86:89], v[164:167], v[206:209], v[86:89]
	v_mfma_f32_16x16x32_bf16 v[82:85], v[182:185], v[206:209], v[82:85]
	v_mfma_f32_16x16x32_bf16 v[70:73], v[164:167], v[214:217], v[70:73]
	v_mfma_f32_16x16x32_bf16 v[66:69], v[182:185], v[214:217], v[66:69]
	v_mfma_f32_16x16x32_bf16 v[134:137], v[168:171], v[194:197], v[134:137]
	v_mfma_f32_16x16x32_bf16 v[130:133], v[186:189], v[194:197], v[130:133]
	v_mfma_f32_16x16x32_bf16 v[118:121], v[168:171], v[202:205], v[118:121]
	v_mfma_f32_16x16x32_bf16 v[114:117], v[186:189], v[202:205], v[114:117]
	v_mfma_f32_16x16x32_bf16 v[86:89], v[168:171], v[210:213], v[86:89]
	v_mfma_f32_16x16x32_bf16 v[82:85], v[186:189], v[210:213], v[82:85]
	v_mfma_f32_16x16x32_bf16 v[70:73], v[168:171], v[218:221], v[70:73]
	s_setprio 0
	v_mfma_f32_16x16x32_bf16 v[66:69], v[186:189], v[218:221], v[66:69]
	s_barrier
	s_add_i32 s30, s59, s33
	v_lshl_add_u64 v[222:223], v[222:223], 0, s[8:9]
	s_mov_b32 m0, s30
	ds_read_b128 v[190:193], v177 offset:49152
	ds_read_b128 v[194:197], v177 offset:50176
	ds_read_b128 v[198:201], v177 offset:51200
	ds_read_b128 v[202:205], v177 offset:52224
	ds_read_b128 v[206:209], v177 offset:53248
	ds_read_b128 v[210:213], v177 offset:54272
	ds_read_b128 v[214:217], v177 offset:55296
	ds_read_b128 v[218:221], v177 offset:56320
	global_load_lds_dwordx4 v[222:223], off
	s_add_i32 m0, s30, 0x2000
	s_add_u32 s28, s28, 0x80080
	v_lshl_add_u64 v[222:223], v[224:225], 0, s[8:9]
	s_addc_u32 s29, s29, 0
	s_add_i32 s30, s68, s33
	global_load_lds_dwordx4 v[222:223], off
	v_lshl_add_u64 v[222:223], s[28:29], 0, v[152:153]
	s_mov_b32 m0, s30
	s_nop 0
	global_load_lds_dwordx4 v[222:223], off
	v_lshl_add_u64 v[222:223], s[28:29], 0, v[148:149]
	s_add_i32 m0, s30, 0x2000
	s_nop 0
	global_load_lds_dwordx4 v[222:223], off
	v_lshl_add_u64 v[222:223], v[226:227], 0, s[8:9]
	s_mov_b32 m0, s41
	s_nop 0
	global_load_lds_dwordx4 v[222:223], off
	v_lshl_add_u64 v[222:223], v[228:229], 0, s[8:9]
	s_mov_b32 m0, s42
	s_nop 0
	global_load_lds_dwordx4 v[222:223], off
	s_waitcnt vmcnt(8)
	s_waitcnt lgkmcnt(0)
	s_setprio 1
	s_barrier
	v_mfma_f32_16x16x32_bf16 v[62:65], v[98:101], v[190:193], v[62:65]
	v_mfma_f32_16x16x32_bf16 v[58:61], v[106:109], v[190:193], v[58:61]
	v_mfma_f32_16x16x32_bf16 v[46:49], v[98:101], v[198:201], v[46:49]
	v_mfma_f32_16x16x32_bf16 v[42:45], v[106:109], v[198:201], v[42:45]
	v_mfma_f32_16x16x32_bf16 v[30:33], v[98:101], v[206:209], v[30:33]
	v_mfma_f32_16x16x32_bf16 v[26:29], v[106:109], v[206:209], v[26:29]
	v_mfma_f32_16x16x32_bf16 v[14:17], v[98:101], v[214:217], v[14:17]
	v_mfma_f32_16x16x32_bf16 v[10:13], v[106:109], v[214:217], v[10:13]
	v_mfma_f32_16x16x32_bf16 v[62:65], v[102:105], v[194:197], v[62:65]
	v_mfma_f32_16x16x32_bf16 v[58:61], v[110:113], v[194:197], v[58:61]
	v_mfma_f32_16x16x32_bf16 v[46:49], v[102:105], v[202:205], v[46:49]
	v_mfma_f32_16x16x32_bf16 v[42:45], v[110:113], v[202:205], v[42:45]
	v_mfma_f32_16x16x32_bf16 v[30:33], v[102:105], v[210:213], v[30:33]
	v_mfma_f32_16x16x32_bf16 v[26:29], v[110:113], v[210:213], v[26:29]
	v_mfma_f32_16x16x32_bf16 v[14:17], v[102:105], v[218:221], v[14:17]
	v_mfma_f32_16x16x32_bf16 v[10:13], v[110:113], v[218:221], v[10:13]
	v_mfma_f32_16x16x32_bf16 v[54:57], v[164:167], v[190:193], v[54:57]
	v_mfma_f32_16x16x32_bf16 v[50:53], v[182:185], v[190:193], v[50:53]
	v_mfma_f32_16x16x32_bf16 v[38:41], v[164:167], v[198:201], v[38:41]
	v_mfma_f32_16x16x32_bf16 v[34:37], v[182:185], v[198:201], v[34:37]
	v_mfma_f32_16x16x32_bf16 v[22:25], v[164:167], v[206:209], v[22:25]
	v_mfma_f32_16x16x32_bf16 v[18:21], v[182:185], v[206:209], v[18:21]
	v_mfma_f32_16x16x32_bf16 v[6:9], v[164:167], v[214:217], v[6:9]
	v_mfma_f32_16x16x32_bf16 v[2:5], v[182:185], v[214:217], v[2:5]
	v_mfma_f32_16x16x32_bf16 v[54:57], v[168:171], v[194:197], v[54:57]
	v_mfma_f32_16x16x32_bf16 v[50:53], v[186:189], v[194:197], v[50:53]
	v_mfma_f32_16x16x32_bf16 v[38:41], v[168:171], v[202:205], v[38:41]
	v_mfma_f32_16x16x32_bf16 v[34:37], v[186:189], v[202:205], v[34:37]
	v_mfma_f32_16x16x32_bf16 v[22:25], v[168:171], v[210:213], v[22:25]
	v_mfma_f32_16x16x32_bf16 v[18:21], v[186:189], v[210:213], v[18:21]
	v_mfma_f32_16x16x32_bf16 v[6:9], v[168:171], v[218:221], v[6:9]
	s_setprio 0
	v_mfma_f32_16x16x32_bf16 v[2:5], v[186:189], v[218:221], v[2:5]
	s_barrier
	s_add_i32 s58, s58, 2
	s_add_u32 s26, s26, 0x100
	s_addc_u32 s27, s27, 0
	s_add_u32 s56, s56, 0x100
	s_addc_u32 s57, s57, 0
	s_cmp_gt_u32 s58, 29
	s_cbranch_scc0 .LBB0_1208
	s_and_b64 vcc, exec, s[16:17]
	s_cbranch_vccz .LBB0_1211
	s_barrier

.LBB0_1284:
	ds_read_b128 v[122:125], v173
	ds_read_b128 v[126:129], v173 offset:1024
	ds_read_b128 v[130:133], v173 offset:2048
	ds_read_b128 v[134:137], v173 offset:3072
	ds_read_b128 v[164:167], v174
	ds_read_b128 v[180:183], v174 offset:1024
	ds_read_b128 v[184:187], v174 offset:2048
	ds_read_b128 v[188:191], v174 offset:3072
	s_add_u32 s28, s26, 0x100
	s_addc_u32 s29, s27, 0
	s_cmpk_eq_i32 s60, 0x54
	s_cselect_b32 s35, s5, s29
	s_cselect_b32 s34, s4, s28
	s_cselect_b32 s31, s25, s59
	s_cselect_b32 s30, s24, s58
	v_lshl_add_u64 v[168:169], s[26:27], 0, v[156:157]
	s_add_i32 m0, s38, 0xc000
	ds_read_b128 v[192:195], v175
	ds_read_b128 v[196:199], v175 offset:1024
	ds_read_b128 v[200:203], v175 offset:2048
	ds_read_b128 v[204:207], v175 offset:3072
	ds_read_b128 v[208:211], v175 offset:4096
	ds_read_b128 v[212:215], v175 offset:5120
	ds_read_b128 v[216:219], v175 offset:6144
	ds_read_b128 v[220:223], v175 offset:7168
	global_load_lds_dwordx4 v[168:169], off
	v_lshl_add_u64 v[168:169], s[26:27], 0, v[158:159]
	s_add_i32 m0, s38, 0xe000
	s_nop 0
	global_load_lds_dwordx4 v[168:169], off
	s_waitcnt vmcnt(8)
	s_waitcnt lgkmcnt(0)
	s_setprio 1
	s_barrier
	v_mfma_f32_16x16x32_bf16 v[142:145], v[122:125], v[192:195], v[142:145]
	v_mfma_f32_16x16x32_bf16 v[138:141], v[130:133], v[192:195], v[138:141]
	v_mfma_f32_16x16x32_bf16 v[110:113], v[122:125], v[200:203], v[110:113]
	v_mfma_f32_16x16x32_bf16 v[106:109], v[130:133], v[200:203], v[106:109]
	v_mfma_f32_16x16x32_bf16 v[94:97], v[122:125], v[208:211], v[94:97]
	v_mfma_f32_16x16x32_bf16 v[90:93], v[130:133], v[208:211], v[90:93]
	v_mfma_f32_16x16x32_bf16 v[78:81], v[122:125], v[216:219], v[78:81]
	v_mfma_f32_16x16x32_bf16 v[74:77], v[130:133], v[216:219], v[74:77]
	v_mfma_f32_16x16x32_bf16 v[142:145], v[126:129], v[196:199], v[142:145]
	v_mfma_f32_16x16x32_bf16 v[138:141], v[134:137], v[196:199], v[138:141]
	v_mfma_f32_16x16x32_bf16 v[110:113], v[126:129], v[204:207], v[110:113]
	v_mfma_f32_16x16x32_bf16 v[106:109], v[134:137], v[204:207], v[106:109]
	v_mfma_f32_16x16x32_bf16 v[94:97], v[126:129], v[212:215], v[94:97]
	v_mfma_f32_16x16x32_bf16 v[90:93], v[134:137], v[212:215], v[90:93]
	v_mfma_f32_16x16x32_bf16 v[78:81], v[126:129], v[220:223], v[78:81]
	v_mfma_f32_16x16x32_bf16 v[74:77], v[134:137], v[220:223], v[74:77]
	v_mfma_f32_16x16x32_bf16 v[118:121], v[164:167], v[192:195], v[118:121]
	v_mfma_f32_16x16x32_bf16 v[114:117], v[184:187], v[192:195], v[114:117]
	v_mfma_f32_16x16x32_bf16 v[102:105], v[164:167], v[200:203], v[102:105]
	v_mfma_f32_16x16x32_bf16 v[98:101], v[184:187], v[200:203], v[98:101]
	v_mfma_f32_16x16x32_bf16 v[86:89], v[164:167], v[208:211], v[86:89]
	v_mfma_f32_16x16x32_bf16 v[82:85], v[184:187], v[208:211], v[82:85]
	v_mfma_f32_16x16x32_bf16 v[70:73], v[164:167], v[216:219], v[70:73]
	v_mfma_f32_16x16x32_bf16 v[66:69], v[184:187], v[216:219], v[66:69]
	v_mfma_f32_16x16x32_bf16 v[118:121], v[180:183], v[196:199], v[118:121]
	v_mfma_f32_16x16x32_bf16 v[114:117], v[188:191], v[196:199], v[114:117]
	v_mfma_f32_16x16x32_bf16 v[102:105], v[180:183], v[204:207], v[102:105]
	v_mfma_f32_16x16x32_bf16 v[98:101], v[188:191], v[204:207], v[98:101]
	v_mfma_f32_16x16x32_bf16 v[86:89], v[180:183], v[212:215], v[86:89]
	v_mfma_f32_16x16x32_bf16 v[82:85], v[188:191], v[212:215], v[82:85]
	v_mfma_f32_16x16x32_bf16 v[70:73], v[180:183], v[220:223], v[70:73]
	s_setprio 0
	v_mfma_f32_16x16x32_bf16 v[66:69], v[188:191], v[220:223], v[66:69]
	s_barrier
	s_add_i32 s26, s48, s33
	v_lshl_add_u64 v[168:169], s[30:31], 0, v[152:153]
	s_mov_b32 m0, s26
	ds_read_b128 v[192:195], v175 offset:16384
	ds_read_b128 v[196:199], v175 offset:17408
	ds_read_b128 v[200:203], v175 offset:18432
	ds_read_b128 v[204:207], v175 offset:19456
	ds_read_b128 v[208:211], v175 offset:20480
	ds_read_b128 v[212:215], v175 offset:21504
	ds_read_b128 v[216:219], v175 offset:22528
	ds_read_b128 v[220:223], v175 offset:23552
	global_load_lds_dwordx4 v[168:169], off
	s_add_i32 m0, s26, 0x2000
	s_add_u32 s26, s30, 0x160000
	v_lshl_add_u64 v[176:177], s[30:31], 0, v[148:149]
	s_addc_u32 s27, s31, 0
	s_add_i32 s61, s49, s33
	global_load_lds_dwordx4 v[176:177], off
	v_lshl_add_u64 v[224:225], s[26:27], 0, v[152:153]
	s_mov_b32 m0, s61
	v_lshl_add_u64 v[226:227], s[34:35], 0, v[150:151]
	global_load_lds_dwordx4 v[224:225], off
	v_lshl_add_u64 v[224:225], s[26:27], 0, v[148:149]
	s_add_i32 m0, s61, 0x2000
	s_nop 0
	global_load_lds_dwordx4 v[224:225], off
	v_lshl_add_u64 v[224:225], s[34:35], 0, v[154:155]
	s_mov_b32 m0, s38
	s_nop 0
	global_load_lds_dwordx4 v[224:225], off
	s_mov_b32 m0, s39
	s_nop 0
	global_load_lds_dwordx4 v[226:227], off
	s_waitcnt vmcnt(8)
	s_waitcnt lgkmcnt(0)
	s_setprio 1
	s_barrier
	v_mfma_f32_16x16x32_bf16 v[62:65], v[122:125], v[192:195], v[62:65]
	v_mfma_f32_16x16x32_bf16 v[58:61], v[130:133], v[192:195], v[58:61]
	v_mfma_f32_16x16x32_bf16 v[46:49], v[122:125], v[200:203], v[46:49]
	v_mfma_f32_16x16x32_bf16 v[42:45], v[130:133], v[200:203], v[42:45]
	v_mfma_f32_16x16x32_bf16 v[30:33], v[122:125], v[208:211], v[30:33]
	v_mfma_f32_16x16x32_bf16 v[26:29], v[130:133], v[208:211], v[26:29]
	v_mfma_f32_16x16x32_bf16 v[14:17], v[122:125], v[216:219], v[14:17]
	v_mfma_f32_16x16x32_bf16 v[10:13], v[130:133], v[216:219], v[10:13]
	v_mfma_f32_16x16x32_bf16 v[62:65], v[126:129], v[196:199], v[62:65]
	v_mfma_f32_16x16x32_bf16 v[58:61], v[134:137], v[196:199], v[58:61]
	v_mfma_f32_16x16x32_bf16 v[46:49], v[126:129], v[204:207], v[46:49]
	v_mfma_f32_16x16x32_bf16 v[42:45], v[134:137], v[204:207], v[42:45]
	v_mfma_f32_16x16x32_bf16 v[30:33], v[126:129], v[212:215], v[30:33]
	v_mfma_f32_16x16x32_bf16 v[26:29], v[134:137], v[212:215], v[26:29]
	v_mfma_f32_16x16x32_bf16 v[14:17], v[126:129], v[220:223], v[14:17]
	v_mfma_f32_16x16x32_bf16 v[10:13], v[134:137], v[220:223], v[10:13]
	v_mfma_f32_16x16x32_bf16 v[54:57], v[164:167], v[192:195], v[54:57]
	v_mfma_f32_16x16x32_bf16 v[50:53], v[184:187], v[192:195], v[50:53]
	v_mfma_f32_16x16x32_bf16 v[38:41], v[164:167], v[200:203], v[38:41]
	v_mfma_f32_16x16x32_bf16 v[34:37], v[184:187], v[200:203], v[34:37]
	v_mfma_f32_16x16x32_bf16 v[22:25], v[164:167], v[208:211], v[22:25]
	v_mfma_f32_16x16x32_bf16 v[18:21], v[184:187], v[208:211], v[18:21]
	v_mfma_f32_16x16x32_bf16 v[6:9], v[164:167], v[216:219], v[6:9]
	v_mfma_f32_16x16x32_bf16 v[2:5], v[184:187], v[216:219], v[2:5]
	v_mfma_f32_16x16x32_bf16 v[54:57], v[180:183], v[196:199], v[54:57]
	v_mfma_f32_16x16x32_bf16 v[50:53], v[188:191], v[196:199], v[50:53]
	v_mfma_f32_16x16x32_bf16 v[38:41], v[180:183], v[204:207], v[38:41]
	v_mfma_f32_16x16x32_bf16 v[34:37], v[188:191], v[204:207], v[34:37]
	v_mfma_f32_16x16x32_bf16 v[22:25], v[180:183], v[212:215], v[22:25]
	v_mfma_f32_16x16x32_bf16 v[18:21], v[188:191], v[212:215], v[18:21]
	v_mfma_f32_16x16x32_bf16 v[6:9], v[180:183], v[220:223], v[6:9]
	s_setprio 0
	v_mfma_f32_16x16x32_bf16 v[2:5], v[188:191], v[220:223], v[2:5]
	s_barrier
	s_add_i32 s61, 0, 0x18000
	s_add_i32 s68, 0, 0x1c000
	v_add_u32_e32 v134, s61, v171
	v_add_u32_e32 v179, s68, v171
	ds_read_b128 v[122:125], v134
	ds_read_b128 v[126:129], v134 offset:1024
	ds_read_b128 v[130:133], v134 offset:2048
	ds_read_b128 v[134:137], v134 offset:3072
	ds_read_b128 v[164:167], v179
	ds_read_b128 v[180:183], v179 offset:1024
	ds_read_b128 v[184:187], v179 offset:2048
	ds_read_b128 v[188:191], v179 offset:3072
	s_add_u32 s26, s34, 0x160000
	s_addc_u32 s27, s35, 0
	s_mov_b32 m0, s40
	v_lshl_add_u64 v[228:229], s[26:27], 0, v[154:155]
	ds_read_b128 v[192:195], v175 offset:32768
	ds_read_b128 v[196:199], v175 offset:33792
	ds_read_b128 v[200:203], v175 offset:34816
	ds_read_b128 v[204:207], v175 offset:35840
	ds_read_b128 v[208:211], v175 offset:36864
	ds_read_b128 v[212:215], v175 offset:37888
	ds_read_b128 v[216:219], v175 offset:38912
	ds_read_b128 v[220:223], v175 offset:39936
	global_load_lds_dwordx4 v[228:229], off
	v_lshl_add_u64 v[228:229], s[26:27], 0, v[150:151]
	s_mov_b32 m0, s41
	s_nop 0
	global_load_lds_dwordx4 v[228:229], off
	s_waitcnt vmcnt(8)
	s_waitcnt lgkmcnt(0)
	s_setprio 1
	s_barrier
	v_mfma_f32_16x16x32_bf16 v[142:145], v[122:125], v[192:195], v[142:145]
	v_mfma_f32_16x16x32_bf16 v[138:141], v[130:133], v[192:195], v[138:141]
	v_mfma_f32_16x16x32_bf16 v[110:113], v[122:125], v[200:203], v[110:113]
	v_mfma_f32_16x16x32_bf16 v[106:109], v[130:133], v[200:203], v[106:109]
	v_mfma_f32_16x16x32_bf16 v[94:97], v[122:125], v[208:211], v[94:97]
	v_mfma_f32_16x16x32_bf16 v[90:93], v[130:133], v[208:211], v[90:93]
	v_mfma_f32_16x16x32_bf16 v[78:81], v[122:125], v[216:219], v[78:81]
	v_mfma_f32_16x16x32_bf16 v[74:77], v[130:133], v[216:219], v[74:77]
	v_mfma_f32_16x16x32_bf16 v[142:145], v[126:129], v[196:199], v[142:145]
	v_mfma_f32_16x16x32_bf16 v[138:141], v[134:137], v[196:199], v[138:141]
	v_mfma_f32_16x16x32_bf16 v[110:113], v[126:129], v[204:207], v[110:113]
	v_mfma_f32_16x16x32_bf16 v[106:109], v[134:137], v[204:207], v[106:109]
	v_mfma_f32_16x16x32_bf16 v[94:97], v[126:129], v[212:215], v[94:97]
	v_mfma_f32_16x16x32_bf16 v[90:93], v[134:137], v[212:215], v[90:93]
	v_mfma_f32_16x16x32_bf16 v[78:81], v[126:129], v[220:223], v[78:81]
	v_mfma_f32_16x16x32_bf16 v[74:77], v[134:137], v[220:223], v[74:77]
	v_mfma_f32_16x16x32_bf16 v[118:121], v[164:167], v[192:195], v[118:121]
	v_mfma_f32_16x16x32_bf16 v[114:117], v[184:187], v[192:195], v[114:117]
	v_mfma_f32_16x16x32_bf16 v[102:105], v[164:167], v[200:203], v[102:105]
	v_mfma_f32_16x16x32_bf16 v[98:101], v[184:187], v[200:203], v[98:101]
	v_mfma_f32_16x16x32_bf16 v[86:89], v[164:167], v[208:211], v[86:89]
	v_mfma_f32_16x16x32_bf16 v[82:85], v[184:187], v[208:211], v[82:85]
	v_mfma_f32_16x16x32_bf16 v[70:73], v[164:167], v[216:219], v[70:73]
	v_mfma_f32_16x16x32_bf16 v[66:69], v[184:187], v[216:219], v[66:69]
	v_mfma_f32_16x16x32_bf16 v[118:121], v[180:183], v[196:199], v[118:121]
	v_mfma_f32_16x16x32_bf16 v[114:117], v[188:191], v[196:199], v[114:117]
	v_mfma_f32_16x16x32_bf16 v[102:105], v[180:183], v[204:207], v[102:105]
	v_mfma_f32_16x16x32_bf16 v[98:101], v[188:191], v[204:207], v[98:101]
	v_mfma_f32_16x16x32_bf16 v[86:89], v[180:183], v[212:215], v[86:89]
	v_mfma_f32_16x16x32_bf16 v[82:85], v[188:191], v[212:215], v[82:85]
	v_mfma_f32_16x16x32_bf16 v[70:73], v[180:183], v[220:223], v[70:73]
	s_setprio 0
	v_mfma_f32_16x16x32_bf16 v[66:69], v[188:191], v[220:223], v[66:69]
	s_barrier
	s_add_i32 s26, s61, s33
	v_lshl_add_u64 v[168:169], v[168:169], 0, s[8:9]
	s_mov_b32 m0, s26
	ds_read_b128 v[192:195], v175 offset:49152
	ds_read_b128 v[196:199], v175 offset:50176
	ds_read_b128 v[200:203], v175 offset:51200
	ds_read_b128 v[204:207], v175 offset:52224
	ds_read_b128 v[208:211], v175 offset:53248
	ds_read_b128 v[212:215], v175 offset:54272
	ds_read_b128 v[216:219], v175 offset:55296
	ds_read_b128 v[220:223], v175 offset:56320
	global_load_lds_dwordx4 v[168:169], off
	s_add_i32 m0, s26, 0x2000
	s_add_u32 s26, s30, 0x160080
	v_lshl_add_u64 v[168:169], v[176:177], 0, s[8:9]
	s_addc_u32 s27, s31, 0
	s_add_i32 s30, s68, s33
	global_load_lds_dwordx4 v[168:169], off
	v_lshl_add_u64 v[168:169], s[26:27], 0, v[152:153]
	s_mov_b32 m0, s30
	s_nop 0
	global_load_lds_dwordx4 v[168:169], off
	v_lshl_add_u64 v[168:169], s[26:27], 0, v[148:149]
	s_add_i32 m0, s30, 0x2000
	s_nop 0
	global_load_lds_dwordx4 v[168:169], off
	v_lshl_add_u64 v[168:169], v[224:225], 0, s[8:9]
	s_mov_b32 m0, s43
	s_nop 0
	global_load_lds_dwordx4 v[168:169], off
	v_lshl_add_u64 v[168:169], v[226:227], 0, s[8:9]
	s_mov_b32 m0, s44
	s_nop 0
	global_load_lds_dwordx4 v[168:169], off
	s_waitcnt vmcnt(8)
	s_waitcnt lgkmcnt(0)
	s_setprio 1
	s_barrier
	v_mfma_f32_16x16x32_bf16 v[62:65], v[122:125], v[192:195], v[62:65]
	v_mfma_f32_16x16x32_bf16 v[58:61], v[130:133], v[192:195], v[58:61]
	v_mfma_f32_16x16x32_bf16 v[46:49], v[122:125], v[200:203], v[46:49]
	v_mfma_f32_16x16x32_bf16 v[42:45], v[130:133], v[200:203], v[42:45]
	v_mfma_f32_16x16x32_bf16 v[30:33], v[122:125], v[208:211], v[30:33]
	v_mfma_f32_16x16x32_bf16 v[26:29], v[130:133], v[208:211], v[26:29]
	v_mfma_f32_16x16x32_bf16 v[14:17], v[122:125], v[216:219], v[14:17]
	v_mfma_f32_16x16x32_bf16 v[10:13], v[130:133], v[216:219], v[10:13]
	v_mfma_f32_16x16x32_bf16 v[62:65], v[126:129], v[196:199], v[62:65]
	v_mfma_f32_16x16x32_bf16 v[58:61], v[134:137], v[196:199], v[58:61]
	v_mfma_f32_16x16x32_bf16 v[46:49], v[126:129], v[204:207], v[46:49]
	v_mfma_f32_16x16x32_bf16 v[42:45], v[134:137], v[204:207], v[42:45]
	v_mfma_f32_16x16x32_bf16 v[30:33], v[126:129], v[212:215], v[30:33]
	v_mfma_f32_16x16x32_bf16 v[26:29], v[134:137], v[212:215], v[26:29]
	v_mfma_f32_16x16x32_bf16 v[14:17], v[126:129], v[220:223], v[14:17]
	v_mfma_f32_16x16x32_bf16 v[10:13], v[134:137], v[220:223], v[10:13]
	v_mfma_f32_16x16x32_bf16 v[54:57], v[164:167], v[192:195], v[54:57]
	v_mfma_f32_16x16x32_bf16 v[50:53], v[184:187], v[192:195], v[50:53]
	v_mfma_f32_16x16x32_bf16 v[38:41], v[164:167], v[200:203], v[38:41]
	v_mfma_f32_16x16x32_bf16 v[34:37], v[184:187], v[200:203], v[34:37]
	v_mfma_f32_16x16x32_bf16 v[22:25], v[164:167], v[208:211], v[22:25]
	v_mfma_f32_16x16x32_bf16 v[18:21], v[184:187], v[208:211], v[18:21]
	v_mfma_f32_16x16x32_bf16 v[6:9], v[164:167], v[216:219], v[6:9]
	v_mfma_f32_16x16x32_bf16 v[2:5], v[184:187], v[216:219], v[2:5]
	v_mfma_f32_16x16x32_bf16 v[54:57], v[180:183], v[196:199], v[54:57]
	v_mfma_f32_16x16x32_bf16 v[50:53], v[188:191], v[196:199], v[50:53]
	v_mfma_f32_16x16x32_bf16 v[38:41], v[180:183], v[204:207], v[38:41]
	v_mfma_f32_16x16x32_bf16 v[34:37], v[188:191], v[204:207], v[34:37]
	v_mfma_f32_16x16x32_bf16 v[22:25], v[180:183], v[212:215], v[22:25]
	v_mfma_f32_16x16x32_bf16 v[18:21], v[188:191], v[212:215], v[18:21]
	v_mfma_f32_16x16x32_bf16 v[6:9], v[180:183], v[220:223], v[6:9]
	s_setprio 0
	v_mfma_f32_16x16x32_bf16 v[2:5], v[188:191], v[220:223], v[2:5]
	s_barrier
	s_add_i32 s60, s60, 2
	s_add_u32 s58, s58, 0x100
	s_addc_u32 s59, s59, 0
	s_cmpk_gt_u32 s60, 0x55
	s_mov_b64 s[26:27], s[28:29]
	s_cbranch_scc0 .LBB0_1284
	s_and_b64 vcc, exec, s[12:13]
	s_cbranch_vccz .LBB0_1287
	s_barrier
